# attention: PV operands swapped (O^T accumulators), per-lane rescale, LDS-transposed full-line epilogue stores, no s_setprio
# speedup vs baseline: 1.0029x; 1.0029x over previous
; __device__ __forceinline__ unsigned cvt_pk_bf16(float lo, float hi) { unsigned r; asm volatile("v_cvt_pk_bf16_f32 %0, %1, %2" : "=v"(r) : "v"(lo), "v"(hi)); return r; }
; __device__ __forceinline__ int crow(int r, int hi) { return (r & 3) + 8 * (r >> 2) + 4 * hi; }
; #define PPBAR() do { ATT_SBAR(); asm volatile("s_waitcnt lgkmcnt(0)" ::: "memory"); __builtin_amdgcn_s_barrier(); asm volatile("" ::: "memory"); ATT_SBAR(); } while (0)
; template <int DK, bool CAUSAL> ...
;     ...
;     {
;         int t2 = threadIdx.x; asm volatile("" : "+v"(t2));
;         const int wid2 = t2 >> 6, r2 = t2 & 31, hi2 = (t2 >> 5) & 1;
;         float* li2 = (float*)(lds + 2 * SHM_V + 2 * SHM_K) + wid2 * 64;
;         if (hi2 == 0) li2[r2] = l_reg; asm volatile("s_waitcnt lgkmcnt(0)" ::: "memory");
;         bf16_t* Ow = O + (size_t)(wid2 * QBLK) * ldo + r2;
; #pragma unroll
;         for (int r = 0; r < 16; ++r) { const int orow = crow(r, hi2); const float rl = __builtin_amdgcn_rcpf(li2[orow]);
; #pragma unroll
;             for (int d0 = 0; d0 < 4; ++d0) { const unsigned w = cvt_pk_bf16(o[d0][r] * rl, 0.f); Ow[(size_t)orow * ldo + d0 * 32] = (bf16_t)(w & 0xffffu); } }
;     }
;     PPBAR();
.LBB0_781:
	s_waitcnt lgkmcnt(0)
	s_barrier
	s_mov_b64 s[6:7], 0
	s_and_b64 vcc, exec, s[64:65]
	s_cbranch_vccnz .LBB0_779

; #define ATT_SBAR() __builtin_amdgcn_sched_barrier(0)
; __device__ __forceinline__ int crow(int r, int hi) { return (r & 3) + 8 * (r >> 2) + 4 * hi; }
; #define QP_LD(d, s) do { ka[s] = *reinterpret_cast<const bf16x8*>(r0 + (d) * 32); kb[s] = *reinterpret_cast<const bf16x8*>(r1 + (d) * 32); } while (0)
; #define QP_LD(d, s) do { ka[s] = *reinterpret_cast<const bf16x8*>(r0 + (d) * 32); kb[s] = *reinterpret_cast<const bf16x8*>(r1 + (d) * 32); } while (0)
; template <int DK> __device__ __forceinline__ void qkt_pipe(f32x16& p0, f32x16& p1, const char* Ks, const bf16x8* qr, int r32, int hi) {
;     constexpr int ND = DK / 16, KR = DK * 2 + 16;
;     const char* r0 = Ks + ATT_KSWZ(r32, hi * 16, KR); const char* r1 = Ks + ATT_KSWZ(32 + r32, hi * 16, KR);
;     bf16x8 ka[3], kb[3];
;     ...
;     QP_LD(0, 0); QP_LD(1, 1); QP_LD(2, 2); ATT_SBAR();
;     p0 = f32x16{}; p1 = f32x16{};
;     __builtin_amdgcn_s_setprio(1);
; #pragma unroll
;     for (int d0 = 0; d0 < ND; ++d0) {
;         p0 = __builtin_amdgcn_mfma_f32_32x32x16_bf16(ka[d0 % 3], qr[d0], p0, 0, 0, 0);
;         p1 = __builtin_amdgcn_mfma_f32_32x32x16_bf16(kb[d0 % 3], qr[d0], p1, 0, 0, 0);
;         if (d0 + 3 < ND) QP_LD(d0 + 3, d0 % 3);
;         ATT_SBAR(); }
;     __builtin_amdgcn_s_setprio(0);
; __device__ __forceinline__ void cmask(f32x16& p0, f32x16& p1, int t, int qrel, int hi) {
;     const float ninf = -__builtin_inff();
; #pragma unroll
;     for (int r = 0; r < 16; ++r) { const int k0 = 64 * t + crow(r, hi); if (k0 > qrel) p0[r] = ninf; if (k0 + 32 > qrel) p1[r] = ninf; }
; }
.LBB0_786:
	v_and_b32_e32 v201, 31, v58
	v_bfe_u32 v0, v58, 5, 1
	v_mul_u32_u24_e32 v2, 0x190, v201
	v_lshlrev_b32_e32 v189, 4, v0
	v_add3_u32 v195, 0, v2, v189
	ds_read_b128 v[2:5], v195 offset:32768
	ds_read_b128 v[6:9], v195 offset:32800
	ds_read_b128 v[10:13], v195 offset:45568
	ds_read_b128 v[14:17], v195 offset:32832
	ds_read_b128 v[50:53], v195 offset:45600
	ds_read_b128 v[54:57], v195 offset:45632
	s_ashr_i32 s82, s10, 6
	s_waitcnt lgkmcnt(5)
	v_mfma_f32_32x32x16_bf16 v[34:49], v[2:5], v[98:101], 0
	ds_read_b128 v[2:5], v195 offset:32864
	ds_read_b128 v[60:63], v195 offset:45664
	s_waitcnt lgkmcnt(5)
	v_mfma_f32_32x32x16_bf16 v[18:33], v[10:13], v[98:101], 0
	v_mfma_f32_32x32x16_bf16 v[34:49], v[6:9], v[102:105], v[34:49]
	ds_read_b128 v[6:9], v195 offset:32896
	ds_read_b128 v[10:13], v195 offset:45696
	s_waitcnt lgkmcnt(5)
	v_mfma_f32_32x32x16_bf16 v[18:33], v[50:53], v[102:105], v[18:33]
	v_mfma_f32_32x32x16_bf16 v[34:49], v[14:17], v[106:109], v[34:49]
	ds_read_b128 v[14:17], v195 offset:32928
	ds_read_b128 v[50:53], v195 offset:45728
	s_waitcnt lgkmcnt(6)
	v_mfma_f32_32x32x16_bf16 v[18:33], v[54:57], v[106:109], v[18:33]
	s_waitcnt lgkmcnt(5)
	v_mfma_f32_32x32x16_bf16 v[34:49], v[2:5], v[110:113], v[34:49]
	ds_read_b128 v[2:5], v195 offset:32960
	ds_read_b128 v[54:57], v195 offset:45760
	s_waitcnt lgkmcnt(6)
	v_mfma_f32_32x32x16_bf16 v[18:33], v[60:63], v[110:113], v[18:33]
	s_waitcnt lgkmcnt(5)
	v_mfma_f32_32x32x16_bf16 v[34:49], v[6:9], v[114:117], v[34:49]
	ds_read_b128 v[6:9], v195 offset:32992
	ds_read_b128 v[60:63], v195 offset:45792
	s_waitcnt lgkmcnt(6)
	v_mfma_f32_32x32x16_bf16 v[18:33], v[10:13], v[114:117], v[18:33]
	s_waitcnt lgkmcnt(5)
	v_mfma_f32_32x32x16_bf16 v[34:49], v[14:17], v[118:121], v[34:49]
	ds_read_b128 v[10:13], v195 offset:33024
	ds_read_b128 v[14:17], v195 offset:45824
	s_waitcnt lgkmcnt(6)
	v_mfma_f32_32x32x16_bf16 v[18:33], v[50:53], v[118:121], v[18:33]
	s_waitcnt lgkmcnt(5)
	v_mfma_f32_32x32x16_bf16 v[34:49], v[2:5], v[122:125], v[34:49]
	ds_read_b128 v[2:5], v195 offset:33056
	ds_read_b128 v[50:53], v195 offset:45856
	s_waitcnt lgkmcnt(6)
	v_mfma_f32_32x32x16_bf16 v[18:33], v[54:57], v[122:125], v[18:33]
	s_waitcnt lgkmcnt(5)
	v_mfma_f32_32x32x16_bf16 v[34:49], v[6:9], v[126:129], v[34:49]
	ds_read_b128 v[6:9], v195 offset:33088
	ds_read_b128 v[54:57], v195 offset:45888
	s_waitcnt lgkmcnt(6)
	v_mfma_f32_32x32x16_bf16 v[18:33], v[60:63], v[126:129], v[18:33]
	s_waitcnt lgkmcnt(5)
	v_mfma_f32_32x32x16_bf16 v[34:49], v[10:13], v[130:133], v[34:49]
	ds_read_b128 v[10:13], v195 offset:33120
	ds_read_b128 v[60:63], v195 offset:45920
	s_waitcnt lgkmcnt(6)
	v_mfma_f32_32x32x16_bf16 v[18:33], v[14:17], v[130:133], v[18:33]
	s_waitcnt lgkmcnt(5)
	v_mfma_f32_32x32x16_bf16 v[34:49], v[2:5], v[158:161], v[34:49]
	s_waitcnt lgkmcnt(4)
	v_mfma_f32_32x32x16_bf16 v[18:33], v[50:53], v[158:161], v[18:33]
	s_waitcnt lgkmcnt(3)
	v_mfma_f32_32x32x16_bf16 v[34:49], v[6:9], v[134:137], v[34:49]
	s_waitcnt lgkmcnt(2)
	v_mfma_f32_32x32x16_bf16 v[18:33], v[54:57], v[134:137], v[18:33]
	s_waitcnt lgkmcnt(1)
	v_mfma_f32_32x32x16_bf16 v[34:49], v[10:13], v[162:165], v[34:49]
	s_waitcnt lgkmcnt(0)
	v_mfma_f32_32x32x16_bf16 v[18:33], v[60:63], v[162:165], v[18:33]
	s_waitcnt lgkmcnt(0)
	s_barrier
	s_cmp_eq_u32 s0, 0
	s_cselect_b64 s[66:67], -1, 0
	s_cmp_lt_i32 s82, 2
	s_cselect_b64 s[0:1], -1, 0
	s_and_b64 s[0:1], s[66:67], s[0:1]
	s_andn2_b64 vcc, exec, s[0:1]
	v_lshlrev_b32_e32 v196, 2, v0
	v_lshl_or_b32 v203, s82, 5, v201
	s_cbranch_vccnz .LBB0_788
	v_or_b32_e32 v0, 32, v196
	v_cmp_le_i32_e32 vcc, v0, v203
	v_or_b32_e32 v0, 33, v196
	s_nop 0
	v_cndmask_b32_e32 v18, v190, v18, vcc
	v_cmp_lt_i32_e32 vcc, v196, v203
	s_nop 1
	v_cndmask_b32_e32 v35, v190, v35, vcc
	v_cmp_le_i32_e32 vcc, v196, v203
	s_nop 1
	v_cndmask_b32_e32 v34, v190, v34, vcc
	v_cmp_le_i32_e32 vcc, v0, v203
	v_or_b32_e32 v0, 2, v196
	s_nop 0
	v_cndmask_b32_e32 v19, v190, v19, vcc
	v_cmp_le_i32_e32 vcc, v0, v203
	v_or_b32_e32 v0, 34, v196
	s_nop 0
	v_cndmask_b32_e32 v36, v190, v36, vcc
	v_cmp_le_i32_e32 vcc, v0, v203
	v_or_b32_e32 v0, 3, v196
	s_nop 0
	v_cndmask_b32_e32 v20, v190, v20, vcc
	v_cmp_le_i32_e32 vcc, v0, v203
	v_or_b32_e32 v0, 35, v196
	s_nop 0
	v_cndmask_b32_e32 v37, v190, v37, vcc
	v_cmp_le_i32_e32 vcc, v0, v203
	v_or_b32_e32 v0, 8, v196
	s_nop 0
	v_cndmask_b32_e32 v21, v190, v21, vcc
	v_cmp_le_i32_e32 vcc, v0, v203
	v_or_b32_e32 v0, 40, v196
	s_nop 0
	v_cndmask_b32_e32 v38, v190, v38, vcc
	v_cmp_le_i32_e32 vcc, v0, v203
	v_or_b32_e32 v0, 9, v196
	s_nop 0
	v_cndmask_b32_e32 v22, v190, v22, vcc
	v_cmp_le_i32_e32 vcc, v0, v203
	v_or_b32_e32 v0, 41, v196
	s_nop 0
	v_cndmask_b32_e32 v39, v190, v39, vcc
	v_cmp_le_i32_e32 vcc, v0, v203
	v_or_b32_e32 v0, 10, v196
	s_nop 0
	v_cndmask_b32_e32 v23, v190, v23, vcc
	v_cmp_le_i32_e32 vcc, v0, v203
	v_or_b32_e32 v0, 42, v196
	s_nop 0
	v_cndmask_b32_e32 v40, v190, v40, vcc
	v_cmp_le_i32_e32 vcc, v0, v203
	v_or_b32_e32 v0, 11, v196
	s_nop 0
	v_cndmask_b32_e32 v24, v190, v24, vcc
	v_cmp_le_i32_e32 vcc, v0, v203
	v_or_b32_e32 v0, 43, v196
	s_nop 0
	v_cndmask_b32_e32 v41, v190, v41, vcc
	v_cmp_le_i32_e32 vcc, v0, v203
	v_or_b32_e32 v0, 16, v196
	s_nop 0
	v_cndmask_b32_e32 v25, v190, v25, vcc
	v_cmp_le_i32_e32 vcc, v0, v203
	v_or_b32_e32 v0, 48, v196
	s_nop 0
	v_cndmask_b32_e32 v42, v190, v42, vcc
	v_cmp_le_i32_e32 vcc, v0, v203
	v_or_b32_e32 v0, 17, v196
	s_nop 0
	v_cndmask_b32_e32 v26, v190, v26, vcc
	v_cmp_le_i32_e32 vcc, v0, v203
	v_or_b32_e32 v0, 49, v196
	s_nop 0
	v_cndmask_b32_e32 v43, v190, v43, vcc
	v_cmp_le_i32_e32 vcc, v0, v203
	v_or_b32_e32 v0, 18, v196
	s_nop 0
	v_cndmask_b32_e32 v27, v190, v27, vcc
	v_cmp_le_i32_e32 vcc, v0, v203
	v_or_b32_e32 v0, 50, v196
	s_nop 0
	v_cndmask_b32_e32 v44, v190, v44, vcc
	v_cmp_le_i32_e32 vcc, v0, v203
	v_or_b32_e32 v0, 19, v196
	s_nop 0
	v_cndmask_b32_e32 v28, v190, v28, vcc
	v_cmp_le_i32_e32 vcc, v0, v203
	v_or_b32_e32 v0, 51, v196
	s_nop 0
	v_cndmask_b32_e32 v45, v190, v45, vcc
	v_cmp_le_i32_e32 vcc, v0, v203
	v_or_b32_e32 v0, 24, v196
	s_nop 0
	v_cndmask_b32_e32 v29, v190, v29, vcc
	v_cmp_le_i32_e32 vcc, v0, v203
	v_or_b32_e32 v0, 56, v196
	s_nop 0
	v_cndmask_b32_e32 v46, v190, v46, vcc
	v_cmp_le_i32_e32 vcc, v0, v203
	v_or_b32_e32 v0, 25, v196
	s_nop 0
	v_cndmask_b32_e32 v30, v190, v30, vcc
	v_cmp_le_i32_e32 vcc, v0, v203
	v_or_b32_e32 v0, 57, v196
	s_nop 0
	v_cndmask_b32_e32 v47, v190, v47, vcc
	v_cmp_le_i32_e32 vcc, v0, v203
	v_or_b32_e32 v0, 26, v196
	s_nop 0
	v_cndmask_b32_e32 v31, v190, v31, vcc
	v_cmp_le_i32_e32 vcc, v0, v203
	v_or_b32_e32 v0, 58, v196
	s_nop 0
	v_cndmask_b32_e32 v48, v190, v48, vcc
	v_cmp_le_i32_e32 vcc, v0, v203
	v_or_b32_e32 v0, 27, v196
	s_nop 0
	v_cndmask_b32_e32 v32, v190, v32, vcc
	v_cmp_le_i32_e32 vcc, v0, v203
	v_or_b32_e32 v0, 59, v196
	s_nop 0
	v_cndmask_b32_e32 v49, v190, v49, vcc
	v_cmp_le_i32_e32 vcc, v0, v203
	s_nop 1
	v_cndmask_b32_e32 v33, v190, v33, vcc
; __device__ __forceinline__ void partialSM(f32x16& p0, f32x16& p1, float& m_reg, float& mn, float& alpha) {
;     float pmax = p0[0];
; #pragma unroll
;     for (int r = 1; r < 16; ++r) pmax = fmaxf(pmax, p0[r]);
; #pragma unroll
;     for (int r = 0; r < 16; ++r) pmax = fmaxf(pmax, p1[r]);
;     { auto rr = __builtin_amdgcn_permlane32_swap(__float_as_uint(pmax), __float_as_uint(pmax), false, false);
;       pmax = fmaxf(__uint_as_float(rr[0]), __uint_as_float(rr[1])); }
;     if (__builtin_expect(__all(pmax - m_reg <= THR2), 1)) { mn = m_reg; alpha = 1.f; }
;     else { mn = fmaxf(m_reg, pmax); alpha = __builtin_amdgcn_exp2f(m_reg - mn); m_reg = mn; }
.LBB0_788:
	v_max_f32_e32 v0, v35, v35
	v_max_f32_e32 v2, v34, v34
	v_max_f32_e32 v0, v2, v0
	v_max3_f32 v0, v0, v36, v37
	v_max3_f32 v0, v0, v38, v39
	v_max3_f32 v0, v0, v40, v41
	v_max3_f32 v0, v0, v42, v43
	v_max3_f32 v0, v0, v44, v45
	v_max3_f32 v0, v0, v46, v47
	v_max3_f32 v0, v0, v48, v49
	v_max3_f32 v0, v0, v18, v19
	v_max3_f32 v0, v0, v20, v21
	v_max3_f32 v0, v0, v22, v23
	v_max3_f32 v0, v0, v24, v25
	v_max3_f32 v0, v0, v26, v27
	v_max3_f32 v0, v0, v28, v29
	v_max3_f32 v0, v0, v30, v31
	v_max3_f32 v0, v0, v32, v33
	v_mov_b32_e32 v2, v0
	s_nop 1
	v_permlane32_swap_b32_e32 v0, v2
	v_max_f32_e32 v2, v2, v2
	v_max_f32_e32 v0, v0, v0
	v_max_f32_e32 v0, v0, v2
	s_and_b32 s0, s10, 0x3fffffc0
	v_max_f32_e32 v50, 0xf149f2ca, v0
	s_lshl_b32 s0, s0, 2
	v_add_f32_e32 v2, 0x7149f2ca, v0
	v_sub_f32_e32 v0, 0xf149f2ca, v50
	s_add_i32 s13, s0, 0
	v_exp_f32_e32 v0, v0
	s_add_i32 s13, s13, 0x14800
	v_cmp_ge_f32_e32 vcc, s77, v2
	s_cmp_eq_u64 vcc, exec
	s_cselect_b64 s[4:5], -1, 0
	v_and_b32_e32 v202, 63, v58
	v_cndmask_b32_e64 v199, v0, 1.0, s[4:5]
	v_cmp_gt_f32_e32 vcc, 1.0, v199
	v_cmp_gt_u32_e64 s[0:1], 32, v202
	s_cbranch_vccz .LBB0_794
	s_branch .LBB0_794

; #define ATT_SBAR() __builtin_amdgcn_sched_barrier(0)
; #define QP_LD(d, s) do { ka[s] = *reinterpret_cast<const bf16x8*>(r0 + (d) * 32); kb[s] = *reinterpret_cast<const bf16x8*>(r1 + (d) * 32); } while (0)
; #define ATT_TRB(vb, off) __builtin_amdgcn_ds_read_tr16_b64_v4i16((LAS s16x4*)(unsigned)((vb) + (off)))
; #define QP_LD(d, s) do { ka[s] = *reinterpret_cast<const bf16x8*>(r0 + (d) * 32); kb[s] = *reinterpret_cast<const bf16x8*>(r1 + (d) * 32); } while (0)
; template <int DK> __device__ __forceinline__ void qkt_pipe_pv(f32x16& p0, f32x16& p1, const char* Ks, const bf16x8* qr, int r32, int hi, int vb, s16x4 (&F)[8]) {
;     constexpr int ND = DK / 16, KR = DK * 2 + 16;
;     const char* r0 = Ks + ATT_KSWZ(r32, hi * 16, KR); const char* r1 = Ks + ATT_KSWZ(32 + r32, hi * 16, KR);
;     bf16x8 ka[3], kb[3];
;     ...
;     QP_LD(0, 0); QP_LD(1, 1); QP_LD(2, 2); ATT_SBAR();
;     p0 = f32x16{}; p1 = f32x16{};
;     __builtin_amdgcn_s_setprio(1);
; #pragma unroll
;     for (int d0 = 0; d0 < ND; ++d0) {
;         p0 = __builtin_amdgcn_mfma_f32_32x32x16_bf16(ka[d0 % 3], qr[d0], p0, 0, 0, 0);
;         p1 = __builtin_amdgcn_mfma_f32_32x32x16_bf16(kb[d0 % 3], qr[d0], p1, 0, 0, 0);
;         if (d0 + 3 < ND) QP_LD(d0 + 3, d0 % 3);
;         if (d0 == ND - 3) { F[0] = ATT_TRB(vb, v_rd_off(0, 0, 0)); F[1] = ATT_TRB(vb, v_rd_off(0, 0, 1)); F[2] = ATT_TRB(vb, v_rd_off(0, 1, 0)); F[3] = ATT_TRB(vb, v_rd_off(0, 1, 1)); }
;         if (d0 == ND - 2) { F[4] = ATT_TRB(vb, v_rd_off(0, 2, 0)); F[5] = ATT_TRB(vb, v_rd_off(0, 2, 1)); F[6] = ATT_TRB(vb, v_rd_off(0, 3, 0)); F[7] = ATT_TRB(vb, v_rd_off(0, 3, 1)); }
;         ATT_SBAR(); }
;     __builtin_amdgcn_s_setprio(0);
;     ...
; }
; __device__ __forceinline__ void pv_d0_pre(f32x16* o, int vb, bf16x8 pa0, bf16x8 pa1, bf16x8 pa2, bf16x8 pa3, s16x4 (&F)[8]) {
;     s16x4 G[8];
;     ...
;     PVB_RD(1, G); ATT_SBAR(); PVB_MM(0, F); ATT_SBAR();
;     PVB_RD(2, F); ATT_SBAR(); PVB_MM(1, G); ATT_SBAR();
;     PVB_RD(3, G); ATT_SBAR(); PVB_MM(2, F); ATT_SBAR();
;     PVB_MM(3, G);
;     ...
; }
.LBB0_803:
	v_lshlrev_b32_e32 v18, 4, v202
	v_lshlrev_b32_e32 v0, 3, v202
	v_and_b32_e32 v18, 0xc0, v18
	v_lshlrev_b32_e32 v19, 1, v202
	v_and_or_b32 v18, v0, 24, v18
	v_and_b32_e32 v19, 32, v19
	v_and_b32_e32 v0, 0x100, v0
	v_or3_b32 v0, v18, v19, v0
	s_waitcnt lgkmcnt(0)
	s_barrier
	v_add_u32_e32 v198, 0xe400, v195
	ds_read_b128 v[18:21], v195 offset:58368
	ds_read_b128 v[22:25], v195 offset:58400
	ds_read_b128 v[26:29], v198 offset:12800
	ds_read_b128 v[30:33], v195 offset:58432
	ds_read_b128 v[34:37], v198 offset:12832
	ds_read_b128 v[38:41], v198 offset:12864
	s_waitcnt lgkmcnt(5)
	v_mfma_f32_32x32x16_bf16 v[82:97], v[18:21], v[98:101], 0
	ds_read_b128 v[18:21], v195 offset:58464
	ds_read_b128 v[42:45], v198 offset:12896
	s_cmp_lg_u32 0, -1
	s_cselect_b32 s0, 0, 0
	s_waitcnt lgkmcnt(5)
	v_mfma_f32_32x32x16_bf16 v[66:81], v[26:29], v[98:101], 0
	v_mfma_f32_32x32x16_bf16 v[82:97], v[22:25], v[102:105], v[82:97]
	ds_read_b128 v[22:25], v195 offset:58496
	ds_read_b128 v[26:29], v198 offset:12928
	s_waitcnt lgkmcnt(5)
	v_mfma_f32_32x32x16_bf16 v[66:81], v[34:37], v[102:105], v[66:81]
	v_mfma_f32_32x32x16_bf16 v[82:97], v[30:33], v[106:109], v[82:97]
	ds_read_b128 v[30:33], v195 offset:58528
	ds_read_b128 v[34:37], v198 offset:12960
	s_waitcnt lgkmcnt(6)
	v_mfma_f32_32x32x16_bf16 v[66:81], v[38:41], v[106:109], v[66:81]
	s_waitcnt lgkmcnt(5)
	v_mfma_f32_32x32x16_bf16 v[82:97], v[18:21], v[110:113], v[82:97]
	ds_read_b128 v[18:21], v195 offset:58560
	ds_read_b128 v[38:41], v198 offset:12992
	s_waitcnt lgkmcnt(6)
	v_mfma_f32_32x32x16_bf16 v[66:81], v[42:45], v[110:113], v[66:81]
	s_waitcnt lgkmcnt(5)
	v_mfma_f32_32x32x16_bf16 v[82:97], v[22:25], v[114:117], v[82:97]
	ds_read_b128 v[22:25], v195 offset:58592
	ds_read_b128 v[42:45], v198 offset:13024
	s_waitcnt lgkmcnt(6)
	v_mfma_f32_32x32x16_bf16 v[66:81], v[26:29], v[114:117], v[66:81]
	s_waitcnt lgkmcnt(5)
	v_mfma_f32_32x32x16_bf16 v[82:97], v[30:33], v[118:121], v[82:97]
	ds_read_b128 v[26:29], v195 offset:58624
	ds_read_b128 v[30:33], v198 offset:13056
	s_waitcnt lgkmcnt(6)
	v_mfma_f32_32x32x16_bf16 v[66:81], v[34:37], v[118:121], v[66:81]
	s_waitcnt lgkmcnt(5)
	v_mfma_f32_32x32x16_bf16 v[82:97], v[18:21], v[122:125], v[82:97]
	ds_read_b128 v[18:21], v195 offset:58656
	ds_read_b128 v[34:37], v198 offset:13088
	s_waitcnt lgkmcnt(6)
	v_mfma_f32_32x32x16_bf16 v[66:81], v[38:41], v[122:125], v[66:81]
	s_waitcnt lgkmcnt(5)
	v_mfma_f32_32x32x16_bf16 v[82:97], v[22:25], v[126:129], v[82:97]
	ds_read_b128 v[22:25], v195 offset:58688
	ds_read_b128 v[38:41], v198 offset:13120
	s_waitcnt lgkmcnt(6)
	v_mfma_f32_32x32x16_bf16 v[66:81], v[42:45], v[126:129], v[66:81]
	s_waitcnt lgkmcnt(5)
	v_mfma_f32_32x32x16_bf16 v[82:97], v[26:29], v[130:133], v[82:97]
	ds_read_b128 v[26:29], v195 offset:58720
	ds_read_b128 v[42:45], v198 offset:13152
	s_waitcnt lgkmcnt(6)
	v_mfma_f32_32x32x16_bf16 v[66:81], v[30:33], v[130:133], v[66:81]
	s_waitcnt lgkmcnt(5)
	v_mfma_f32_32x32x16_bf16 v[82:97], v[18:21], v[158:161], v[82:97]
	v_add_u32_e32 v197, 0, v0
	v_add_u32_e32 v0, s0, v0
	ds_read_b64_tr_b16 v[46:47], v197
	ds_read_b64_tr_b16 v[48:49], v0 offset:2048
	ds_read_b64_tr_b16 v[50:51], v0 offset:4096
	ds_read_b64_tr_b16 v[52:53], v0 offset:6144
	s_waitcnt lgkmcnt(8)
	v_mfma_f32_32x32x16_bf16 v[66:81], v[34:37], v[158:161], v[66:81]
	s_waitcnt lgkmcnt(7)
	v_mfma_f32_32x32x16_bf16 v[82:97], v[22:25], v[134:137], v[82:97]
	ds_read_b64_tr_b16 v[34:35], v0 offset:8192
	ds_read_b64_tr_b16 v[36:37], v0 offset:10240
	ds_read_b64_tr_b16 v[54:55], v0 offset:12288
	ds_read_b64_tr_b16 v[56:57], v0 offset:14336
	s_waitcnt lgkmcnt(10)
	v_mfma_f32_32x32x16_bf16 v[66:81], v[38:41], v[134:137], v[66:81]
	s_waitcnt lgkmcnt(9)
	v_mfma_f32_32x32x16_bf16 v[82:97], v[26:29], v[162:165], v[82:97]
	s_waitcnt lgkmcnt(8)
	v_mfma_f32_32x32x16_bf16 v[66:81], v[42:45], v[162:165], v[66:81]
	ds_read_b64_tr_b16 v[58:59], v0 offset:512
	ds_read_b64_tr_b16 v[60:61], v0 offset:2560
	ds_read_b64_tr_b16 v[62:63], v0 offset:4608
	ds_read_b64_tr_b16 v[64:65], v0 offset:6656
	ds_read_b64_tr_b16 v[206:207], v0 offset:8704
	ds_read_b64_tr_b16 v[208:209], v0 offset:10752
	ds_read_b64_tr_b16 v[210:211], v0 offset:12800
	ds_read_b64_tr_b16 v[212:213], v0 offset:14848
	s_waitcnt lgkmcnt(14)
	v_mfma_f32_32x32x16_bf16 v[18:33], v[46:49], v[166:169], v[2:17]
	s_waitcnt lgkmcnt(12)
	v_mfma_f32_32x32x16_bf16 v[18:33], v[50:53], v[170:173], v[18:33]
	s_waitcnt lgkmcnt(10)
	v_mfma_f32_32x32x16_bf16 v[18:33], v[34:37], v[174:177], v[18:33]
	s_waitcnt lgkmcnt(8)
	v_mfma_f32_32x32x16_bf16 v[18:33], v[54:57], v[178:181], v[18:33]
	ds_read_b64_tr_b16 v[214:215], v0 offset:1024
	ds_read_b64_tr_b16 v[216:217], v0 offset:3072
	ds_read_b64_tr_b16 v[218:219], v0 offset:5120
	ds_read_b64_tr_b16 v[220:221], v0 offset:7168
	ds_read_b64_tr_b16 v[222:223], v0 offset:9216
	ds_read_b64_tr_b16 v[224:225], v0 offset:11264
	ds_read_b64_tr_b16 v[226:227], v0 offset:13312
	ds_read_b64_tr_b16 v[228:229], v0 offset:15360
	s_waitcnt lgkmcnt(14)
	v_mfma_f32_32x32x16_bf16 v[34:49], v[58:61], v[166:169], v[2:17]
	s_waitcnt lgkmcnt(12)
	v_mfma_f32_32x32x16_bf16 v[34:49], v[62:65], v[170:173], v[34:49]
	s_waitcnt lgkmcnt(10)
	v_mfma_f32_32x32x16_bf16 v[34:49], v[206:209], v[174:177], v[34:49]
	s_waitcnt lgkmcnt(8)
	v_mfma_f32_32x32x16_bf16 v[34:49], v[210:213], v[178:181], v[34:49]
	ds_read_b64_tr_b16 v[206:207], v0 offset:1536
	ds_read_b64_tr_b16 v[208:209], v0 offset:3584
	ds_read_b64_tr_b16 v[210:211], v0 offset:5632
	ds_read_b64_tr_b16 v[212:213], v0 offset:7680
	ds_read_b64_tr_b16 v[230:231], v0 offset:9728
	ds_read_b64_tr_b16 v[232:233], v0 offset:11776
	ds_read_b64_tr_b16 v[234:235], v0 offset:13824
	ds_read_b64_tr_b16 v[236:237], v0 offset:15872
	s_waitcnt lgkmcnt(14)
	v_mfma_f32_32x32x16_bf16 v[50:65], v[214:217], v[166:169], v[2:17]
	s_waitcnt lgkmcnt(12)
	v_mfma_f32_32x32x16_bf16 v[50:65], v[218:221], v[170:173], v[50:65]
	s_waitcnt lgkmcnt(10)
	v_mfma_f32_32x32x16_bf16 v[50:65], v[222:225], v[174:177], v[50:65]
	s_waitcnt lgkmcnt(8)
	v_mfma_f32_32x32x16_bf16 v[50:65], v[226:229], v[178:181], v[50:65]
	s_waitcnt lgkmcnt(6)
	v_mfma_f32_32x32x16_bf16 v[2:17], v[206:209], v[166:169], v[2:17]
	s_waitcnt lgkmcnt(4)
	v_mfma_f32_32x32x16_bf16 v[2:17], v[210:213], v[170:173], v[2:17]
	s_waitcnt lgkmcnt(2)
	v_mfma_f32_32x32x16_bf16 v[2:17], v[230:233], v[174:177], v[2:17]
	s_waitcnt lgkmcnt(0)
	v_mfma_f32_32x32x16_bf16 v[2:17], v[234:237], v[178:181], v[2:17]
	s_waitcnt lgkmcnt(0)
	s_barrier
; __device__ __forceinline__ int crow(int r, int hi) { return (r & 3) + 8 * (r >> 2) + 4 * hi; }
; __device__ __forceinline__ void partialSM(f32x16& p0, f32x16& p1, float& m_reg, float& mn, float& alpha) {
;     float pmax = p0[0];
; #pragma unroll
;     for (int r = 1; r < 16; ++r) pmax = fmaxf(pmax, p0[r]);
; #pragma unroll
;     for (int r = 0; r < 16; ++r) pmax = fmaxf(pmax, p1[r]);
;     { auto rr = __builtin_amdgcn_permlane32_swap(__float_as_uint(pmax), __float_as_uint(pmax), false, false);
;       pmax = fmaxf(__uint_as_float(rr[0]), __uint_as_float(rr[1])); }
;     if (__builtin_expect(__all(pmax - m_reg <= THR2), 1)) { mn = m_reg; alpha = 1.f; }
;     else { mn = fmaxf(m_reg, pmax); alpha = __builtin_amdgcn_exp2f(m_reg - mn); m_reg = mn; }
; __device__ __forceinline__ void cmask(f32x16& p0, f32x16& p1, int t, int qrel, int hi) {
;     const float ninf = -__builtin_inff();
; #pragma unroll
;     for (int r = 0; r < 16; ++r) { const int k0 = 64 * t + crow(r, hi); if (k0 > qrel) p0[r] = ninf; if (k0 + 32 > qrel) p1[r] = ninf; }
; }
	s_cmp_lt_i32 s82, 4
	s_cselect_b64 s[0:1], -1, 0
	s_and_b64 s[0:1], s[66:67], s[0:1]
	s_andn2_b64 vcc, exec, s[0:1]
	s_cbranch_vccnz .LBB0_805
	v_or_b32_e32 v166, 0x60, v196
	v_or_b32_e32 v0, 64, v196
	v_cmp_le_i32_e32 vcc, v166, v203
	s_nop 1
	v_cndmask_b32_e32 v66, v190, v66, vcc
	v_cmp_lt_i32_e32 vcc, v0, v203
	s_nop 1
	v_cndmask_b32_e32 v83, v190, v83, vcc
	v_cmp_le_i32_e32 vcc, v0, v203
	v_or_b32_e32 v0, 0x61, v196
	s_nop 0
	v_cndmask_b32_e32 v82, v190, v82, vcc
	v_cmp_le_i32_e32 vcc, v0, v203
	v_or_b32_e32 v0, 0x42, v196
	s_nop 0
	v_cndmask_b32_e32 v67, v190, v67, vcc
	v_cmp_le_i32_e32 vcc, v0, v203
	v_or_b32_e32 v0, 0x62, v196
	s_nop 0
	v_cndmask_b32_e32 v84, v190, v84, vcc
	v_cmp_le_i32_e32 vcc, v0, v203
	v_or_b32_e32 v0, 0x43, v196
	s_nop 0
	v_cndmask_b32_e32 v68, v190, v68, vcc
	v_cmp_le_i32_e32 vcc, v0, v203
	v_or_b32_e32 v0, 0x63, v196
	s_nop 0
	v_cndmask_b32_e32 v85, v190, v85, vcc
	v_cmp_le_i32_e32 vcc, v0, v203
	v_or_b32_e32 v0, 0x48, v196
	s_nop 0
	v_cndmask_b32_e32 v69, v190, v69, vcc
	v_cmp_le_i32_e32 vcc, v0, v203
	v_or_b32_e32 v0, 0x68, v196
	s_nop 0
	v_cndmask_b32_e32 v86, v190, v86, vcc
	v_cmp_le_i32_e32 vcc, v0, v203
	v_or_b32_e32 v0, 0x49, v196
	s_nop 0
	v_cndmask_b32_e32 v70, v190, v70, vcc
	v_cmp_le_i32_e32 vcc, v0, v203
	v_or_b32_e32 v0, 0x69, v196
	s_nop 0
	v_cndmask_b32_e32 v87, v190, v87, vcc
	v_cmp_le_i32_e32 vcc, v0, v203
	v_or_b32_e32 v0, 0x4a, v196
	s_nop 0
	v_cndmask_b32_e32 v71, v190, v71, vcc
	v_cmp_le_i32_e32 vcc, v0, v203
	v_or_b32_e32 v0, 0x6a, v196
	s_nop 0
	v_cndmask_b32_e32 v88, v190, v88, vcc
	v_cmp_le_i32_e32 vcc, v0, v203
	v_or_b32_e32 v0, 0x4b, v196
	s_nop 0
	v_cndmask_b32_e32 v72, v190, v72, vcc
	v_cmp_le_i32_e32 vcc, v0, v203
	v_or_b32_e32 v0, 0x6b, v196
	s_nop 0
	v_cndmask_b32_e32 v89, v190, v89, vcc
	v_cmp_le_i32_e32 vcc, v0, v203
	v_or_b32_e32 v0, 0x50, v196
	s_nop 0
	v_cndmask_b32_e32 v73, v190, v73, vcc
	v_cmp_le_i32_e32 vcc, v0, v203
	v_or_b32_e32 v0, 0x70, v196
	s_nop 0
	v_cndmask_b32_e32 v90, v190, v90, vcc
	v_cmp_le_i32_e32 vcc, v0, v203
	v_or_b32_e32 v0, 0x51, v196
	s_nop 0
	v_cndmask_b32_e32 v74, v190, v74, vcc
	v_cmp_le_i32_e32 vcc, v0, v203
	v_or_b32_e32 v0, 0x71, v196
	s_nop 0
	v_cndmask_b32_e32 v91, v190, v91, vcc
	v_cmp_le_i32_e32 vcc, v0, v203
	v_or_b32_e32 v0, 0x52, v196
	s_nop 0
	v_cndmask_b32_e32 v75, v190, v75, vcc
	v_cmp_le_i32_e32 vcc, v0, v203
	v_or_b32_e32 v0, 0x72, v196
	s_nop 0
	v_cndmask_b32_e32 v92, v190, v92, vcc
	v_cmp_le_i32_e32 vcc, v0, v203
	v_or_b32_e32 v0, 0x53, v196
	s_nop 0
	v_cndmask_b32_e32 v76, v190, v76, vcc
	v_cmp_le_i32_e32 vcc, v0, v203
	v_or_b32_e32 v0, 0x73, v196
	s_nop 0
	v_cndmask_b32_e32 v93, v190, v93, vcc
	v_cmp_le_i32_e32 vcc, v0, v203
	v_or_b32_e32 v0, 0x58, v196
	s_nop 0
	v_cndmask_b32_e32 v77, v190, v77, vcc
	v_cmp_le_i32_e32 vcc, v0, v203
	v_or_b32_e32 v0, 0x78, v196
	s_nop 0
	v_cndmask_b32_e32 v94, v190, v94, vcc
	v_cmp_le_i32_e32 vcc, v0, v203
	v_or_b32_e32 v0, 0x59, v196
	s_nop 0
	v_cndmask_b32_e32 v78, v190, v78, vcc
	v_cmp_le_i32_e32 vcc, v0, v203
	v_or_b32_e32 v0, 0x79, v196
	s_nop 0
	v_cndmask_b32_e32 v95, v190, v95, vcc
	v_cmp_le_i32_e32 vcc, v0, v203
	v_or_b32_e32 v0, 0x5a, v196
	s_nop 0
	v_cndmask_b32_e32 v79, v190, v79, vcc
	v_cmp_le_i32_e32 vcc, v0, v203
	v_or_b32_e32 v0, 0x7a, v196
	s_nop 0
	v_cndmask_b32_e32 v96, v190, v96, vcc
	v_cmp_le_i32_e32 vcc, v0, v203
	v_or_b32_e32 v0, 0x5b, v196
	s_nop 0
	v_cndmask_b32_e32 v80, v190, v80, vcc
	v_cmp_le_i32_e32 vcc, v0, v203
	v_or_b32_e32 v0, 0x7b, v196
	s_nop 0
	v_cndmask_b32_e32 v97, v190, v97, vcc
	v_cmp_le_i32_e32 vcc, v0, v203
	s_nop 1
	v_cndmask_b32_e32 v81, v190, v81, vcc
.LBB0_805:
	v_max_f32_e32 v0, v83, v83
	v_max_f32_e32 v166, v82, v82
	v_max_f32_e32 v0, v166, v0
	v_max3_f32 v0, v0, v84, v85
	v_max3_f32 v0, v0, v86, v87
	v_max3_f32 v0, v0, v88, v89
	v_max3_f32 v0, v0, v90, v91
	v_max3_f32 v0, v0, v92, v93
	v_max3_f32 v0, v0, v94, v95
	v_max3_f32 v0, v0, v96, v97
	v_max3_f32 v0, v0, v66, v67
	v_max3_f32 v0, v0, v68, v69
	v_max3_f32 v0, v0, v70, v71
	v_max3_f32 v0, v0, v72, v73
	v_max3_f32 v0, v0, v74, v75
	v_max3_f32 v0, v0, v76, v77
	v_max3_f32 v0, v0, v78, v79
	v_max3_f32 v0, v0, v80, v81
	v_mov_b32_e32 v166, v0
	s_nop 1
	v_permlane32_swap_b32_e32 v0, v166
	v_max_f32_e32 v166, v166, v166
	v_max_f32_e32 v0, v0, v0
	v_max_f32_e32 v0, v0, v166
	v_max_f32_e32 v166, v205, v205
	v_max_f32_e32 v166, v166, v0
	v_sub_f32_e32 v167, v0, v205
	v_sub_f32_e32 v0, v205, v166
	v_exp_f32_e32 v0, v0
	v_cmp_ge_f32_e32 vcc, s77, v167
	s_cmp_eq_u64 vcc, exec
	s_cselect_b64 s[6:7], -1, 0
	v_cndmask_b32_e64 v206, v0, 1.0, s[6:7]
	v_cmp_gt_f32_e32 vcc, 1.0, v206
	s_cbranch_vccz .LBB0_809
	v_pk_mul_f32 v[30:31], v[30:31], v[206:207] op_sel_hi:[1,0]
	v_pk_mul_f32 v[26:27], v[26:27], v[206:207] op_sel_hi:[1,0]
	v_pk_mul_f32 v[22:23], v[22:23], v[206:207] op_sel_hi:[1,0]
	v_pk_mul_f32 v[32:33], v[32:33], v[206:207] op_sel_hi:[1,0]
	v_pk_mul_f32 v[28:29], v[28:29], v[206:207] op_sel_hi:[1,0]
	v_pk_mul_f32 v[24:25], v[24:25], v[206:207] op_sel_hi:[1,0]
	v_pk_mul_f32 v[20:21], v[20:21], v[206:207] op_sel_hi:[1,0]
	v_pk_mul_f32 v[18:19], v[18:19], v[206:207] op_sel_hi:[1,0]
	v_pk_mul_f32 v[46:47], v[46:47], v[206:207] op_sel_hi:[1,0]
	v_pk_mul_f32 v[42:43], v[42:43], v[206:207] op_sel_hi:[1,0]
	v_pk_mul_f32 v[38:39], v[38:39], v[206:207] op_sel_hi:[1,0]
	v_pk_mul_f32 v[48:49], v[48:49], v[206:207] op_sel_hi:[1,0]
	v_pk_mul_f32 v[44:45], v[44:45], v[206:207] op_sel_hi:[1,0]
	v_pk_mul_f32 v[40:41], v[40:41], v[206:207] op_sel_hi:[1,0]
	v_pk_mul_f32 v[36:37], v[36:37], v[206:207] op_sel_hi:[1,0]
	v_pk_mul_f32 v[34:35], v[34:35], v[206:207] op_sel_hi:[1,0]
	v_pk_mul_f32 v[62:63], v[62:63], v[206:207] op_sel_hi:[1,0]
	v_pk_mul_f32 v[58:59], v[58:59], v[206:207] op_sel_hi:[1,0]
	v_pk_mul_f32 v[54:55], v[54:55], v[206:207] op_sel_hi:[1,0]
	v_pk_mul_f32 v[64:65], v[64:65], v[206:207] op_sel_hi:[1,0]
	v_pk_mul_f32 v[60:61], v[60:61], v[206:207] op_sel_hi:[1,0]
	v_pk_mul_f32 v[56:57], v[56:57], v[206:207] op_sel_hi:[1,0]
	v_pk_mul_f32 v[52:53], v[52:53], v[206:207] op_sel_hi:[1,0]
	v_pk_mul_f32 v[50:51], v[50:51], v[206:207] op_sel_hi:[1,0]
	v_pk_mul_f32 v[14:15], v[14:15], v[206:207] op_sel_hi:[1,0]
	v_pk_mul_f32 v[10:11], v[10:11], v[206:207] op_sel_hi:[1,0]
	v_pk_mul_f32 v[6:7], v[6:7], v[206:207] op_sel_hi:[1,0]
	v_pk_mul_f32 v[16:17], v[16:17], v[206:207] op_sel_hi:[1,0]
	v_pk_mul_f32 v[12:13], v[12:13], v[206:207] op_sel_hi:[1,0]
	v_pk_mul_f32 v[8:9], v[8:9], v[206:207] op_sel_hi:[1,0]
	v_pk_mul_f32 v[4:5], v[4:5], v[206:207] op_sel_hi:[1,0]
	v_pk_mul_f32 v[2:3], v[2:3], v[206:207] op_sel_hi:[1,0]

; #define ATT_SBAR() __builtin_amdgcn_sched_barrier(0)
; #define QP_LD(d, s) do { ka[s] = *reinterpret_cast<const bf16x8*>(r0 + (d) * 32); kb[s] = *reinterpret_cast<const bf16x8*>(r1 + (d) * 32); } while (0)
; #define ATT_TRB(vb, off) __builtin_amdgcn_ds_read_tr16_b64_v4i16((LAS s16x4*)(unsigned)((vb) + (off)))
; #define QP_LD(d, s) do { ka[s] = *reinterpret_cast<const bf16x8*>(r0 + (d) * 32); kb[s] = *reinterpret_cast<const bf16x8*>(r1 + (d) * 32); } while (0)
; template <int DK> __device__ __forceinline__ void qkt_pipe_pv(f32x16& p0, f32x16& p1, const char* Ks, const bf16x8* qr, int r32, int hi, int vb, s16x4 (&F)[8]) {
;     constexpr int ND = DK / 16, KR = DK * 2 + 16;
;     const char* r0 = Ks + ATT_KSWZ(r32, hi * 16, KR); const char* r1 = Ks + ATT_KSWZ(32 + r32, hi * 16, KR);
;     bf16x8 ka[3], kb[3];
;     ...
;     QP_LD(0, 0); QP_LD(1, 1); QP_LD(2, 2); ATT_SBAR();
;     p0 = f32x16{}; p1 = f32x16{};
;     __builtin_amdgcn_s_setprio(1);
; #pragma unroll
;     for (int d0 = 0; d0 < ND; ++d0) {
;         p0 = __builtin_amdgcn_mfma_f32_32x32x16_bf16(ka[d0 % 3], qr[d0], p0, 0, 0, 0);
;         p1 = __builtin_amdgcn_mfma_f32_32x32x16_bf16(kb[d0 % 3], qr[d0], p1, 0, 0, 0);
;         if (d0 + 3 < ND) QP_LD(d0 + 3, d0 % 3);
;         if (d0 == ND - 3) { F[0] = ATT_TRB(vb, v_rd_off(0, 0, 0)); F[1] = ATT_TRB(vb, v_rd_off(0, 0, 1)); F[2] = ATT_TRB(vb, v_rd_off(0, 1, 0)); F[3] = ATT_TRB(vb, v_rd_off(0, 1, 1)); }
;         if (d0 == ND - 2) { F[4] = ATT_TRB(vb, v_rd_off(0, 2, 0)); F[5] = ATT_TRB(vb, v_rd_off(0, 2, 1)); F[6] = ATT_TRB(vb, v_rd_off(0, 3, 0)); F[7] = ATT_TRB(vb, v_rd_off(0, 3, 1)); }
;         ATT_SBAR(); }
;     __builtin_amdgcn_s_setprio(0);
;     ...
; }
; __device__ __forceinline__ void pv_d0_pre(f32x16* o, int vb, bf16x8 pa0, bf16x8 pa1, bf16x8 pa2, bf16x8 pa3, s16x4 (&F)[8]) {
;     s16x4 G[8];
;     ...
;     PVB_RD(1, G); ATT_SBAR(); PVB_MM(0, F); ATT_SBAR();
;     PVB_RD(2, F); ATT_SBAR(); PVB_MM(1, G); ATT_SBAR();
;     PVB_RD(3, G); ATT_SBAR(); PVB_MM(2, F); ATT_SBAR();
;     PVB_MM(3, G);
;     ...
; }
.LBB0_819:
	ds_read_b128 v[66:69], v195 offset:32768
	ds_read_b128 v[204:207], v195 offset:32800
	ds_read_b128 v[70:73], v195 offset:45568
	ds_read_b128 v[208:211], v195 offset:32832
	ds_read_b128 v[212:215], v195 offset:45600
	ds_read_b128 v[216:219], v195 offset:45632
	s_waitcnt lgkmcnt(5)
	v_mfma_f32_32x32x16_bf16 v[82:97], v[66:69], v[98:101], 0
	ds_read_b128 v[220:223], v195 offset:32864
	ds_read_b128 v[224:227], v195 offset:45664
	s_waitcnt lgkmcnt(5)
	v_mfma_f32_32x32x16_bf16 v[66:81], v[70:73], v[98:101], 0
	v_mfma_f32_32x32x16_bf16 v[82:97], v[204:207], v[102:105], v[82:97]
	ds_read_b128 v[204:207], v195 offset:32896
	ds_read_b128 v[228:231], v195 offset:45696
	s_waitcnt lgkmcnt(5)
	v_mfma_f32_32x32x16_bf16 v[66:81], v[212:215], v[102:105], v[66:81]
	v_mfma_f32_32x32x16_bf16 v[82:97], v[208:211], v[106:109], v[82:97]
	ds_read_b128 v[208:211], v195 offset:32928
	ds_read_b128 v[212:215], v195 offset:45728
	s_waitcnt lgkmcnt(6)
	v_mfma_f32_32x32x16_bf16 v[66:81], v[216:219], v[106:109], v[66:81]
	s_waitcnt lgkmcnt(5)
	v_mfma_f32_32x32x16_bf16 v[82:97], v[220:223], v[110:113], v[82:97]
	ds_read_b128 v[216:219], v195 offset:32960
	ds_read_b128 v[220:223], v195 offset:45760
	s_waitcnt lgkmcnt(6)
	v_mfma_f32_32x32x16_bf16 v[66:81], v[224:227], v[110:113], v[66:81]
	s_waitcnt lgkmcnt(5)
	v_mfma_f32_32x32x16_bf16 v[82:97], v[204:207], v[114:117], v[82:97]
	ds_read_b128 v[204:207], v195 offset:32992
	ds_read_b128 v[224:227], v195 offset:45792
	s_waitcnt lgkmcnt(6)
	v_mfma_f32_32x32x16_bf16 v[66:81], v[228:231], v[114:117], v[66:81]
	s_waitcnt lgkmcnt(5)
	v_mfma_f32_32x32x16_bf16 v[82:97], v[208:211], v[118:121], v[82:97]
	ds_read_b128 v[208:211], v195 offset:33024
	ds_read_b128 v[228:231], v195 offset:45824
	s_waitcnt lgkmcnt(6)
	v_mfma_f32_32x32x16_bf16 v[66:81], v[212:215], v[118:121], v[66:81]
	s_waitcnt lgkmcnt(5)
	v_mfma_f32_32x32x16_bf16 v[82:97], v[216:219], v[122:125], v[82:97]
	ds_read_b128 v[212:215], v195 offset:33056
	ds_read_b128 v[216:219], v195 offset:45856
	s_waitcnt lgkmcnt(6)
	v_mfma_f32_32x32x16_bf16 v[66:81], v[220:223], v[122:125], v[66:81]
	s_waitcnt lgkmcnt(5)
	v_mfma_f32_32x32x16_bf16 v[82:97], v[204:207], v[126:129], v[82:97]
	ds_read_b128 v[204:207], v195 offset:33088
	ds_read_b128 v[220:223], v195 offset:45888
	s_waitcnt lgkmcnt(6)
	v_mfma_f32_32x32x16_bf16 v[66:81], v[224:227], v[126:129], v[66:81]
	s_waitcnt lgkmcnt(5)
	v_mfma_f32_32x32x16_bf16 v[82:97], v[208:211], v[130:133], v[82:97]
	ds_read_b128 v[208:211], v195 offset:33120
	ds_read_b128 v[224:227], v195 offset:45920
	s_waitcnt lgkmcnt(6)
	v_mfma_f32_32x32x16_bf16 v[66:81], v[228:231], v[130:133], v[66:81]
	s_waitcnt lgkmcnt(5)
	v_mfma_f32_32x32x16_bf16 v[82:97], v[212:215], v[158:161], v[82:97]
	ds_read_b64_tr_b16 v[212:213], v197 offset:16384
	ds_read_b64_tr_b16 v[214:215], v197 offset:18432
	ds_read_b64_tr_b16 v[228:229], v197 offset:20480
	ds_read_b64_tr_b16 v[230:231], v197 offset:22528
	s_waitcnt lgkmcnt(8)
	v_mfma_f32_32x32x16_bf16 v[66:81], v[216:219], v[158:161], v[66:81]
	s_waitcnt lgkmcnt(7)
	v_mfma_f32_32x32x16_bf16 v[82:97], v[204:207], v[134:137], v[82:97]
	ds_read_b64_tr_b16 v[204:205], v197 offset:24576
	ds_read_b64_tr_b16 v[206:207], v197 offset:26624
	ds_read_b64_tr_b16 v[216:217], v197 offset:28672
	ds_read_b64_tr_b16 v[218:219], v197 offset:30720
	s_waitcnt lgkmcnt(10)
	v_mfma_f32_32x32x16_bf16 v[66:81], v[220:223], v[134:137], v[66:81]
	s_waitcnt lgkmcnt(9)
	v_mfma_f32_32x32x16_bf16 v[82:97], v[208:211], v[162:165], v[82:97]
	s_waitcnt lgkmcnt(8)
	v_mfma_f32_32x32x16_bf16 v[66:81], v[224:227], v[162:165], v[66:81]
	ds_read_b64_tr_b16 v[208:209], v197 offset:16896
	ds_read_b64_tr_b16 v[210:211], v197 offset:18944
	ds_read_b64_tr_b16 v[220:221], v197 offset:20992
	ds_read_b64_tr_b16 v[222:223], v197 offset:23040
	ds_read_b64_tr_b16 v[224:225], v197 offset:25088
	ds_read_b64_tr_b16 v[226:227], v197 offset:27136
	ds_read_b64_tr_b16 v[232:233], v197 offset:29184
	ds_read_b64_tr_b16 v[234:235], v197 offset:31232
	s_waitcnt lgkmcnt(14)
	v_mfma_f32_32x32x16_bf16 v[18:33], v[212:215], v[166:169], v[18:33]
	s_waitcnt lgkmcnt(12)
	v_mfma_f32_32x32x16_bf16 v[18:33], v[228:231], v[170:173], v[18:33]
	s_waitcnt lgkmcnt(10)
	v_mfma_f32_32x32x16_bf16 v[18:33], v[204:207], v[174:177], v[18:33]
	s_waitcnt lgkmcnt(8)
	v_mfma_f32_32x32x16_bf16 v[18:33], v[216:219], v[178:181], v[18:33]
	ds_read_b64_tr_b16 v[204:205], v197 offset:17408
	ds_read_b64_tr_b16 v[206:207], v197 offset:19456
	ds_read_b64_tr_b16 v[212:213], v197 offset:21504
	ds_read_b64_tr_b16 v[214:215], v197 offset:23552
	ds_read_b64_tr_b16 v[216:217], v197 offset:25600
	ds_read_b64_tr_b16 v[218:219], v197 offset:27648
	ds_read_b64_tr_b16 v[228:229], v197 offset:29696
	ds_read_b64_tr_b16 v[230:231], v197 offset:31744
	s_waitcnt lgkmcnt(14)
	v_mfma_f32_32x32x16_bf16 v[34:49], v[208:211], v[166:169], v[34:49]
	s_waitcnt lgkmcnt(12)
	v_mfma_f32_32x32x16_bf16 v[34:49], v[220:223], v[170:173], v[34:49]
	s_waitcnt lgkmcnt(10)
	v_mfma_f32_32x32x16_bf16 v[34:49], v[224:227], v[174:177], v[34:49]
	s_waitcnt lgkmcnt(8)
	v_mfma_f32_32x32x16_bf16 v[34:49], v[232:235], v[178:181], v[34:49]
	ds_read_b64_tr_b16 v[208:209], v197 offset:17920
	ds_read_b64_tr_b16 v[210:211], v197 offset:19968
	ds_read_b64_tr_b16 v[220:221], v197 offset:22016
	ds_read_b64_tr_b16 v[222:223], v197 offset:24064
	ds_read_b64_tr_b16 v[224:225], v197 offset:26112
	ds_read_b64_tr_b16 v[226:227], v197 offset:28160
	ds_read_b64_tr_b16 v[232:233], v197 offset:30208
	ds_read_b64_tr_b16 v[234:235], v197 offset:32256
	s_waitcnt lgkmcnt(14)
	v_mfma_f32_32x32x16_bf16 v[50:65], v[204:207], v[166:169], v[50:65]
	s_waitcnt lgkmcnt(12)
	v_mfma_f32_32x32x16_bf16 v[50:65], v[212:215], v[170:173], v[50:65]
	s_waitcnt lgkmcnt(10)
	v_mfma_f32_32x32x16_bf16 v[50:65], v[216:219], v[174:177], v[50:65]
	s_waitcnt lgkmcnt(8)
	v_mfma_f32_32x32x16_bf16 v[50:65], v[228:231], v[178:181], v[50:65]
	s_waitcnt lgkmcnt(6)
	v_mfma_f32_32x32x16_bf16 v[2:17], v[208:211], v[166:169], v[2:17]
	s_waitcnt lgkmcnt(4)
	v_mfma_f32_32x32x16_bf16 v[2:17], v[220:223], v[170:173], v[2:17]
	s_waitcnt lgkmcnt(2)
	v_mfma_f32_32x32x16_bf16 v[2:17], v[224:227], v[174:177], v[2:17]
	s_waitcnt lgkmcnt(0)
	v_mfma_f32_32x32x16_bf16 v[2:17], v[232:235], v[178:181], v[2:17]
	s_waitcnt lgkmcnt(0)
	s_barrier
; __device__ __forceinline__ int crow(int r, int hi) { return (r & 3) + 8 * (r >> 2) + 4 * hi; }
; __device__ __forceinline__ void partialSM(f32x16& p0, f32x16& p1, float& m_reg, float& mn, float& alpha) {
;     float pmax = p0[0];
; #pragma unroll
;     for (int r = 1; r < 16; ++r) pmax = fmaxf(pmax, p0[r]);
; #pragma unroll
;     for (int r = 0; r < 16; ++r) pmax = fmaxf(pmax, p1[r]);
;     { auto rr = __builtin_amdgcn_permlane32_swap(__float_as_uint(pmax), __float_as_uint(pmax), false, false);
;       pmax = fmaxf(__uint_as_float(rr[0]), __uint_as_float(rr[1])); }
;     if (__builtin_expect(__all(pmax - m_reg <= THR2), 1)) { mn = m_reg; alpha = 1.f; }
;     else { mn = fmaxf(m_reg, pmax); alpha = __builtin_amdgcn_exp2f(m_reg - mn); m_reg = mn; }
; __device__ __forceinline__ void cmask(f32x16& p0, f32x16& p1, int t, int qrel, int hi) {
;     const float ninf = -__builtin_inff();
; #pragma unroll
;     for (int r = 0; r < 16; ++r) { const int k0 = 64 * t + crow(r, hi); if (k0 > qrel) p0[r] = ninf; if (k0 + 32 > qrel) p1[r] = ninf; }
; }
	s_add_i32 s8, s90, s86
	s_cmp_lt_i32 s8, 0
	s_cbranch_scc1 .LBB0_822
	s_sub_i32 s0, s58, 64
	s_cmp_le_i32 s0, s83
	s_cbranch_scc1 .LBB0_822
	v_add_u32_e32 v0, s58, v196
	v_add_u32_e32 v167, 0xffffffa1, v0
	v_add_u32_e32 v166, 0xffffff81, v0
	v_cmp_le_i32_e32 vcc, v167, v200
	s_nop 1
	v_cndmask_b32_e32 v66, v190, v66, vcc
	v_cmp_lt_i32_e32 vcc, v166, v200
	s_nop 1
	v_cndmask_b32_e32 v83, v190, v83, vcc
	v_cmp_le_i32_e32 vcc, v166, v200
	v_add_u32_e32 v166, 0xffffffa2, v0
	s_nop 0
	v_cndmask_b32_e32 v82, v190, v82, vcc
	v_cmp_le_i32_e32 vcc, v166, v200
	v_add_u32_e32 v166, 0xffffff83, v0
	s_nop 0
	v_cndmask_b32_e32 v67, v190, v67, vcc
	v_cmp_le_i32_e32 vcc, v166, v200
	v_add_u32_e32 v166, 0xffffffa3, v0
	s_nop 0
	v_cndmask_b32_e32 v84, v190, v84, vcc
	v_cmp_le_i32_e32 vcc, v166, v200
	v_add_u32_e32 v166, 0xffffff84, v0
	s_nop 0
	v_cndmask_b32_e32 v68, v190, v68, vcc
	v_cmp_le_i32_e32 vcc, v166, v200
	v_add_u32_e32 v166, 0xffffffa4, v0
	s_nop 0
	v_cndmask_b32_e32 v85, v190, v85, vcc
	v_cmp_le_i32_e32 vcc, v166, v200
	v_add_u32_e32 v166, 0xffffff89, v0
	s_nop 0
	v_cndmask_b32_e32 v69, v190, v69, vcc
	v_cmp_le_i32_e32 vcc, v166, v200
	v_add_u32_e32 v166, 0xffffffa9, v0
	s_nop 0
	v_cndmask_b32_e32 v86, v190, v86, vcc
	v_cmp_le_i32_e32 vcc, v166, v200
	v_add_u32_e32 v166, 0xffffff8a, v0
	s_nop 0
	v_cndmask_b32_e32 v70, v190, v70, vcc
	v_cmp_le_i32_e32 vcc, v166, v200
	v_add_u32_e32 v166, 0xffffffaa, v0
	s_nop 0
	v_cndmask_b32_e32 v87, v190, v87, vcc
	v_cmp_le_i32_e32 vcc, v166, v200
	v_add_u32_e32 v166, 0xffffff8b, v0
	s_nop 0
	v_cndmask_b32_e32 v71, v190, v71, vcc
	v_cmp_le_i32_e32 vcc, v166, v200
	v_add_u32_e32 v166, 0xffffffab, v0
	s_nop 0
	v_cndmask_b32_e32 v88, v190, v88, vcc
	v_cmp_le_i32_e32 vcc, v166, v200
	v_add_u32_e32 v166, 0xffffff8c, v0
	s_nop 0
	v_cndmask_b32_e32 v72, v190, v72, vcc
	v_cmp_le_i32_e32 vcc, v166, v200
	v_add_u32_e32 v166, 0xffffffac, v0
	s_nop 0
	v_cndmask_b32_e32 v89, v190, v89, vcc
	v_cmp_le_i32_e32 vcc, v166, v200
	v_add_u32_e32 v166, 0xffffff91, v0
	s_nop 0
	v_cndmask_b32_e32 v73, v190, v73, vcc
	v_cmp_le_i32_e32 vcc, v166, v200
	v_add_u32_e32 v166, 0xffffffb1, v0
	s_nop 0
	v_cndmask_b32_e32 v90, v190, v90, vcc
	v_cmp_le_i32_e32 vcc, v166, v200
	v_add_u32_e32 v166, 0xffffff92, v0
	s_nop 0
	v_cndmask_b32_e32 v74, v190, v74, vcc
	v_cmp_le_i32_e32 vcc, v166, v200
	v_add_u32_e32 v166, 0xffffffb2, v0
	s_nop 0
	v_cndmask_b32_e32 v91, v190, v91, vcc
	v_cmp_le_i32_e32 vcc, v166, v200
	v_add_u32_e32 v166, 0xffffff93, v0
	s_nop 0
	v_cndmask_b32_e32 v75, v190, v75, vcc
	v_cmp_le_i32_e32 vcc, v166, v200
	v_add_u32_e32 v166, 0xffffffb3, v0
	s_nop 0
	v_cndmask_b32_e32 v92, v190, v92, vcc
	v_cmp_le_i32_e32 vcc, v166, v200
	v_add_u32_e32 v166, 0xffffff94, v0
	s_nop 0
	v_cndmask_b32_e32 v76, v190, v76, vcc
	v_cmp_le_i32_e32 vcc, v166, v200
	v_add_u32_e32 v166, 0xffffffb4, v0
	s_nop 0
	v_cndmask_b32_e32 v93, v190, v93, vcc
	v_cmp_le_i32_e32 vcc, v166, v200
	v_add_u32_e32 v166, 0xffffff99, v0
	s_nop 0
	v_cndmask_b32_e32 v77, v190, v77, vcc
	v_cmp_le_i32_e32 vcc, v166, v200
	v_add_u32_e32 v166, 0xffffffb9, v0
	s_nop 0
	v_cndmask_b32_e32 v94, v190, v94, vcc
	v_cmp_le_i32_e32 vcc, v166, v200
	v_add_u32_e32 v166, 0xffffff9a, v0
	s_nop 0
	v_cndmask_b32_e32 v78, v190, v78, vcc
	v_cmp_le_i32_e32 vcc, v166, v200
	v_add_u32_e32 v166, 0xffffffba, v0
	s_nop 0
	v_cndmask_b32_e32 v95, v190, v95, vcc
	v_cmp_le_i32_e32 vcc, v166, v200
	v_add_u32_e32 v166, 0xffffff9b, v0
	s_nop 0
	v_cndmask_b32_e32 v79, v190, v79, vcc
	v_cmp_le_i32_e32 vcc, v166, v200
	v_add_u32_e32 v166, 0xffffffbb, v0
	s_nop 0
	v_cndmask_b32_e32 v96, v190, v96, vcc
	v_cmp_le_i32_e32 vcc, v166, v200
	v_add_u32_e32 v166, 0xffffff9c, v0
	v_add_u32_e32 v0, 0xffffffbc, v0
	v_cndmask_b32_e32 v80, v190, v80, vcc
	v_cmp_le_i32_e32 vcc, v166, v200
	s_nop 1
	v_cndmask_b32_e32 v97, v190, v97, vcc
	v_cmp_le_i32_e32 vcc, v0, v200
	s_nop 1
	v_cndmask_b32_e32 v81, v190, v81, vcc
.LBB0_822:
	v_max_f32_e32 v0, v83, v83
	v_max_f32_e32 v166, v82, v82
	v_max_f32_e32 v0, v166, v0
	v_max3_f32 v0, v0, v84, v85
	v_max3_f32 v0, v0, v86, v87
	v_max3_f32 v0, v0, v88, v89
	v_max3_f32 v0, v0, v90, v91
	v_max3_f32 v0, v0, v92, v93
	v_max3_f32 v0, v0, v94, v95
	v_max3_f32 v0, v0, v96, v97
	v_max3_f32 v0, v0, v66, v67
	v_max3_f32 v0, v0, v68, v69
	v_max3_f32 v0, v0, v70, v71
	v_max3_f32 v0, v0, v72, v73
	v_max3_f32 v0, v0, v74, v75
	v_max3_f32 v0, v0, v76, v77
	v_max3_f32 v0, v0, v78, v79
	v_max3_f32 v0, v0, v80, v81
	v_mov_b32_e32 v166, v0
	s_nop 1
	v_permlane32_swap_b32_e32 v0, v166
	v_max_f32_e32 v166, v166, v166
	v_max_f32_e32 v0, v0, v0
	v_max_f32_e32 v0, v0, v166
	v_max_f32_e32 v166, v203, v203
	v_max_f32_e32 v166, v166, v0
	v_sub_f32_e32 v167, v0, v203
	v_sub_f32_e32 v0, v203, v166
	v_exp_f32_e32 v0, v0
	v_cmp_ge_f32_e32 vcc, s77, v167
	s_cmp_eq_u64 vcc, exec
	s_cselect_b64 s[6:7], -1, 0
	v_cndmask_b32_e64 v202, v0, 1.0, s[6:7]
	v_cmp_gt_f32_e32 vcc, 1.0, v202
	s_cbranch_vccz .LBB0_826
	v_pk_mul_f32 v[30:31], v[30:31], v[202:203] op_sel_hi:[1,0]
	v_pk_mul_f32 v[26:27], v[26:27], v[202:203] op_sel_hi:[1,0]
	v_pk_mul_f32 v[22:23], v[22:23], v[202:203] op_sel_hi:[1,0]
	v_pk_mul_f32 v[32:33], v[32:33], v[202:203] op_sel_hi:[1,0]
	v_pk_mul_f32 v[28:29], v[28:29], v[202:203] op_sel_hi:[1,0]
	v_pk_mul_f32 v[24:25], v[24:25], v[202:203] op_sel_hi:[1,0]
	v_pk_mul_f32 v[20:21], v[20:21], v[202:203] op_sel_hi:[1,0]
	v_pk_mul_f32 v[18:19], v[18:19], v[202:203] op_sel_hi:[1,0]
	v_pk_mul_f32 v[46:47], v[46:47], v[202:203] op_sel_hi:[1,0]
	v_pk_mul_f32 v[42:43], v[42:43], v[202:203] op_sel_hi:[1,0]
	v_pk_mul_f32 v[38:39], v[38:39], v[202:203] op_sel_hi:[1,0]
	v_pk_mul_f32 v[48:49], v[48:49], v[202:203] op_sel_hi:[1,0]
	v_pk_mul_f32 v[44:45], v[44:45], v[202:203] op_sel_hi:[1,0]
	v_pk_mul_f32 v[40:41], v[40:41], v[202:203] op_sel_hi:[1,0]
	v_pk_mul_f32 v[36:37], v[36:37], v[202:203] op_sel_hi:[1,0]
	v_pk_mul_f32 v[34:35], v[34:35], v[202:203] op_sel_hi:[1,0]
	v_pk_mul_f32 v[62:63], v[62:63], v[202:203] op_sel_hi:[1,0]
	v_pk_mul_f32 v[58:59], v[58:59], v[202:203] op_sel_hi:[1,0]
	v_pk_mul_f32 v[54:55], v[54:55], v[202:203] op_sel_hi:[1,0]
	v_pk_mul_f32 v[64:65], v[64:65], v[202:203] op_sel_hi:[1,0]
	v_pk_mul_f32 v[60:61], v[60:61], v[202:203] op_sel_hi:[1,0]
	v_pk_mul_f32 v[56:57], v[56:57], v[202:203] op_sel_hi:[1,0]
	v_pk_mul_f32 v[52:53], v[52:53], v[202:203] op_sel_hi:[1,0]
	v_pk_mul_f32 v[50:51], v[50:51], v[202:203] op_sel_hi:[1,0]
	v_pk_mul_f32 v[14:15], v[14:15], v[202:203] op_sel_hi:[1,0]
	v_pk_mul_f32 v[10:11], v[10:11], v[202:203] op_sel_hi:[1,0]
	v_pk_mul_f32 v[6:7], v[6:7], v[202:203] op_sel_hi:[1,0]
	v_pk_mul_f32 v[16:17], v[16:17], v[202:203] op_sel_hi:[1,0]
	v_pk_mul_f32 v[12:13], v[12:13], v[202:203] op_sel_hi:[1,0]
	v_pk_mul_f32 v[8:9], v[8:9], v[202:203] op_sel_hi:[1,0]
	v_pk_mul_f32 v[4:5], v[4:5], v[202:203] op_sel_hi:[1,0]
	v_pk_mul_f32 v[2:3], v[2:3], v[202:203] op_sel_hi:[1,0]

; #define ATT_SBAR() __builtin_amdgcn_sched_barrier(0)
; #define QP_LD(d, s) do { ka[s] = *reinterpret_cast<const bf16x8*>(r0 + (d) * 32); kb[s] = *reinterpret_cast<const bf16x8*>(r1 + (d) * 32); } while (0)
; #define ATT_TRB(vb, off) __builtin_amdgcn_ds_read_tr16_b64_v4i16((LAS s16x4*)(unsigned)((vb) + (off)))
; #define QP_LD(d, s) do { ka[s] = *reinterpret_cast<const bf16x8*>(r0 + (d) * 32); kb[s] = *reinterpret_cast<const bf16x8*>(r1 + (d) * 32); } while (0)
; template <int DK> __device__ __forceinline__ void qkt_pipe_pv(f32x16& p0, f32x16& p1, const char* Ks, const bf16x8* qr, int r32, int hi, int vb, s16x4 (&F)[8]) {
;     constexpr int ND = DK / 16, KR = DK * 2 + 16;
;     const char* r0 = Ks + ATT_KSWZ(r32, hi * 16, KR); const char* r1 = Ks + ATT_KSWZ(32 + r32, hi * 16, KR);
;     bf16x8 ka[3], kb[3];
;     ...
;     QP_LD(0, 0); QP_LD(1, 1); QP_LD(2, 2); ATT_SBAR();
;     p0 = f32x16{}; p1 = f32x16{};
;     __builtin_amdgcn_s_setprio(1);
; #pragma unroll
;     for (int d0 = 0; d0 < ND; ++d0) {
;         p0 = __builtin_amdgcn_mfma_f32_32x32x16_bf16(ka[d0 % 3], qr[d0], p0, 0, 0, 0);
;         p1 = __builtin_amdgcn_mfma_f32_32x32x16_bf16(kb[d0 % 3], qr[d0], p1, 0, 0, 0);
;         if (d0 + 3 < ND) QP_LD(d0 + 3, d0 % 3);
;         if (d0 == ND - 3) { F[0] = ATT_TRB(vb, v_rd_off(0, 0, 0)); F[1] = ATT_TRB(vb, v_rd_off(0, 0, 1)); F[2] = ATT_TRB(vb, v_rd_off(0, 1, 0)); F[3] = ATT_TRB(vb, v_rd_off(0, 1, 1)); }
;         if (d0 == ND - 2) { F[4] = ATT_TRB(vb, v_rd_off(0, 2, 0)); F[5] = ATT_TRB(vb, v_rd_off(0, 2, 1)); F[6] = ATT_TRB(vb, v_rd_off(0, 3, 0)); F[7] = ATT_TRB(vb, v_rd_off(0, 3, 1)); }
;         ATT_SBAR(); }
;     __builtin_amdgcn_s_setprio(0);
;     ...
; }
; __device__ __forceinline__ void pv_d0_pre(f32x16* o, int vb, bf16x8 pa0, bf16x8 pa1, bf16x8 pa2, bf16x8 pa3, s16x4 (&F)[8]) {
;     s16x4 G[8];
;     ...
;     PVB_RD(1, G); ATT_SBAR(); PVB_MM(0, F); ATT_SBAR();
;     PVB_RD(2, F); ATT_SBAR(); PVB_MM(1, G); ATT_SBAR();
;     PVB_RD(3, G); ATT_SBAR(); PVB_MM(2, F); ATT_SBAR();
;     PVB_MM(3, G);
;     ...
; }
.LBB0_834:
	s_waitcnt lgkmcnt(0)
	s_barrier
	ds_read_b128 v[66:69], v195 offset:58368
	ds_read_b128 v[206:209], v195 offset:58400
	ds_read_b128 v[70:73], v198 offset:12800
	ds_read_b128 v[210:213], v195 offset:58432
	ds_read_b128 v[214:217], v198 offset:12832
	ds_read_b128 v[218:221], v198 offset:12864
	s_waitcnt lgkmcnt(5)
	v_mfma_f32_32x32x16_bf16 v[82:97], v[66:69], v[98:101], 0
	ds_read_b128 v[222:225], v195 offset:58464
	ds_read_b128 v[226:229], v198 offset:12896
	s_waitcnt lgkmcnt(5)
	v_mfma_f32_32x32x16_bf16 v[66:81], v[70:73], v[98:101], 0
	v_mfma_f32_32x32x16_bf16 v[82:97], v[206:209], v[102:105], v[82:97]
	ds_read_b128 v[206:209], v195 offset:58496
	ds_read_b128 v[230:233], v198 offset:12928
	s_waitcnt lgkmcnt(5)
	v_mfma_f32_32x32x16_bf16 v[66:81], v[214:217], v[102:105], v[66:81]
	v_mfma_f32_32x32x16_bf16 v[82:97], v[210:213], v[106:109], v[82:97]
	ds_read_b128 v[210:213], v195 offset:58528
	ds_read_b128 v[214:217], v198 offset:12960
	s_waitcnt lgkmcnt(6)
	v_mfma_f32_32x32x16_bf16 v[66:81], v[218:221], v[106:109], v[66:81]
	s_waitcnt lgkmcnt(5)
	v_mfma_f32_32x32x16_bf16 v[82:97], v[222:225], v[110:113], v[82:97]
	ds_read_b128 v[218:221], v195 offset:58560
	ds_read_b128 v[222:225], v198 offset:12992
	s_waitcnt lgkmcnt(6)
	v_mfma_f32_32x32x16_bf16 v[66:81], v[226:229], v[110:113], v[66:81]
	s_waitcnt lgkmcnt(5)
	v_mfma_f32_32x32x16_bf16 v[82:97], v[206:209], v[114:117], v[82:97]
	ds_read_b128 v[206:209], v195 offset:58592
	ds_read_b128 v[226:229], v198 offset:13024
	s_waitcnt lgkmcnt(6)
	v_mfma_f32_32x32x16_bf16 v[66:81], v[230:233], v[114:117], v[66:81]
	s_waitcnt lgkmcnt(5)
	v_mfma_f32_32x32x16_bf16 v[82:97], v[210:213], v[118:121], v[82:97]
	ds_read_b128 v[210:213], v195 offset:58624
	ds_read_b128 v[230:233], v198 offset:13056
	s_waitcnt lgkmcnt(6)
	v_mfma_f32_32x32x16_bf16 v[66:81], v[214:217], v[118:121], v[66:81]
	s_waitcnt lgkmcnt(5)
	v_mfma_f32_32x32x16_bf16 v[82:97], v[218:221], v[122:125], v[82:97]
	ds_read_b128 v[214:217], v195 offset:58656
	ds_read_b128 v[218:221], v198 offset:13088
	s_waitcnt lgkmcnt(6)
	v_mfma_f32_32x32x16_bf16 v[66:81], v[222:225], v[122:125], v[66:81]
	s_waitcnt lgkmcnt(5)
	v_mfma_f32_32x32x16_bf16 v[82:97], v[206:209], v[126:129], v[82:97]
	ds_read_b128 v[206:209], v195 offset:58688
	ds_read_b128 v[222:225], v198 offset:13120
	s_waitcnt lgkmcnt(6)
	v_mfma_f32_32x32x16_bf16 v[66:81], v[226:229], v[126:129], v[66:81]
	s_waitcnt lgkmcnt(5)
	v_mfma_f32_32x32x16_bf16 v[82:97], v[210:213], v[130:133], v[82:97]
	ds_read_b128 v[210:213], v195 offset:58720
	ds_read_b128 v[226:229], v198 offset:13152
	s_waitcnt lgkmcnt(6)
	v_mfma_f32_32x32x16_bf16 v[66:81], v[230:233], v[130:133], v[66:81]
	s_waitcnt lgkmcnt(5)
	v_mfma_f32_32x32x16_bf16 v[82:97], v[214:217], v[158:161], v[82:97]
	ds_read_b64_tr_b16 v[214:215], v197
	ds_read_b64_tr_b16 v[216:217], v197 offset:2048
	ds_read_b64_tr_b16 v[230:231], v197 offset:4096
	ds_read_b64_tr_b16 v[232:233], v197 offset:6144
	s_waitcnt lgkmcnt(8)
	v_mfma_f32_32x32x16_bf16 v[66:81], v[218:221], v[158:161], v[66:81]
	s_waitcnt lgkmcnt(7)
	v_mfma_f32_32x32x16_bf16 v[82:97], v[206:209], v[134:137], v[82:97]
	ds_read_b64_tr_b16 v[206:207], v197 offset:8192
	ds_read_b64_tr_b16 v[208:209], v197 offset:10240
	ds_read_b64_tr_b16 v[218:219], v197 offset:12288
	ds_read_b64_tr_b16 v[220:221], v197 offset:14336
	s_waitcnt lgkmcnt(10)
	v_mfma_f32_32x32x16_bf16 v[66:81], v[222:225], v[134:137], v[66:81]
	s_waitcnt lgkmcnt(9)
	v_mfma_f32_32x32x16_bf16 v[82:97], v[210:213], v[162:165], v[82:97]
	s_waitcnt lgkmcnt(8)
	v_mfma_f32_32x32x16_bf16 v[66:81], v[226:229], v[162:165], v[66:81]
	ds_read_b64_tr_b16 v[210:211], v197 offset:512
	ds_read_b64_tr_b16 v[212:213], v197 offset:2560
	ds_read_b64_tr_b16 v[222:223], v197 offset:4608
	ds_read_b64_tr_b16 v[224:225], v197 offset:6656
	ds_read_b64_tr_b16 v[226:227], v197 offset:8704
	ds_read_b64_tr_b16 v[228:229], v197 offset:10752
	ds_read_b64_tr_b16 v[234:235], v197 offset:12800
	ds_read_b64_tr_b16 v[236:237], v197 offset:14848
	s_waitcnt lgkmcnt(14)
	v_mfma_f32_32x32x16_bf16 v[18:33], v[214:217], v[166:169], v[18:33]
	s_waitcnt lgkmcnt(12)
	v_mfma_f32_32x32x16_bf16 v[18:33], v[230:233], v[170:173], v[18:33]
	s_waitcnt lgkmcnt(10)
	v_mfma_f32_32x32x16_bf16 v[18:33], v[206:209], v[174:177], v[18:33]
	s_waitcnt lgkmcnt(8)
	v_mfma_f32_32x32x16_bf16 v[18:33], v[218:221], v[178:181], v[18:33]
	ds_read_b64_tr_b16 v[206:207], v197 offset:1024
	ds_read_b64_tr_b16 v[208:209], v197 offset:3072
	ds_read_b64_tr_b16 v[214:215], v197 offset:5120
	ds_read_b64_tr_b16 v[216:217], v197 offset:7168
	ds_read_b64_tr_b16 v[218:219], v197 offset:9216
	ds_read_b64_tr_b16 v[220:221], v197 offset:11264
	ds_read_b64_tr_b16 v[230:231], v197 offset:13312
	ds_read_b64_tr_b16 v[232:233], v197 offset:15360
	s_waitcnt lgkmcnt(14)
	v_mfma_f32_32x32x16_bf16 v[34:49], v[210:213], v[166:169], v[34:49]
	s_waitcnt lgkmcnt(12)
	v_mfma_f32_32x32x16_bf16 v[34:49], v[222:225], v[170:173], v[34:49]
	s_waitcnt lgkmcnt(10)
	v_mfma_f32_32x32x16_bf16 v[34:49], v[226:229], v[174:177], v[34:49]
	s_waitcnt lgkmcnt(8)
	v_mfma_f32_32x32x16_bf16 v[34:49], v[234:237], v[178:181], v[34:49]
	ds_read_b64_tr_b16 v[210:211], v197 offset:1536
	ds_read_b64_tr_b16 v[212:213], v197 offset:3584
	ds_read_b64_tr_b16 v[222:223], v197 offset:5632
	ds_read_b64_tr_b16 v[224:225], v197 offset:7680
	ds_read_b64_tr_b16 v[226:227], v197 offset:9728
	ds_read_b64_tr_b16 v[228:229], v197 offset:11776
	ds_read_b64_tr_b16 v[234:235], v197 offset:13824
	ds_read_b64_tr_b16 v[236:237], v197 offset:15872
	s_waitcnt lgkmcnt(14)
	v_mfma_f32_32x32x16_bf16 v[50:65], v[206:209], v[166:169], v[50:65]
	s_waitcnt lgkmcnt(12)
	v_mfma_f32_32x32x16_bf16 v[50:65], v[214:217], v[170:173], v[50:65]
	s_waitcnt lgkmcnt(10)
	v_mfma_f32_32x32x16_bf16 v[50:65], v[218:221], v[174:177], v[50:65]
	s_waitcnt lgkmcnt(8)
	v_mfma_f32_32x32x16_bf16 v[50:65], v[230:233], v[178:181], v[50:65]
	s_waitcnt lgkmcnt(6)
	v_mfma_f32_32x32x16_bf16 v[2:17], v[210:213], v[166:169], v[2:17]
	s_waitcnt lgkmcnt(4)
	v_mfma_f32_32x32x16_bf16 v[2:17], v[222:225], v[170:173], v[2:17]
	s_waitcnt lgkmcnt(2)
	v_mfma_f32_32x32x16_bf16 v[2:17], v[226:229], v[174:177], v[2:17]
	s_waitcnt lgkmcnt(0)
	v_mfma_f32_32x32x16_bf16 v[2:17], v[234:237], v[178:181], v[2:17]
	s_waitcnt lgkmcnt(0)
	s_barrier
; __device__ __forceinline__ int crow(int r, int hi) { return (r & 3) + 8 * (r >> 2) + 4 * hi; }
; __device__ __forceinline__ void partialSM(f32x16& p0, f32x16& p1, float& m_reg, float& mn, float& alpha) {
;     float pmax = p0[0];
; #pragma unroll
;     for (int r = 1; r < 16; ++r) pmax = fmaxf(pmax, p0[r]);
; #pragma unroll
;     for (int r = 0; r < 16; ++r) pmax = fmaxf(pmax, p1[r]);
;     { auto rr = __builtin_amdgcn_permlane32_swap(__float_as_uint(pmax), __float_as_uint(pmax), false, false);
;       pmax = fmaxf(__uint_as_float(rr[0]), __uint_as_float(rr[1])); }
;     if (__builtin_expect(__all(pmax - m_reg <= THR2), 1)) { mn = m_reg; alpha = 1.f; }
;     else { mn = fmaxf(m_reg, pmax); alpha = __builtin_amdgcn_exp2f(m_reg - mn); m_reg = mn; }
; __device__ __forceinline__ void cmask(f32x16& p0, f32x16& p1, int t, int qrel, int hi) {
;     const float ninf = -__builtin_inff();
; #pragma unroll
;     for (int r = 0; r < 16; ++r) { const int k0 = 64 * t + crow(r, hi); if (k0 > qrel) p0[r] = ninf; if (k0 + 32 > qrel) p1[r] = ninf; }
; }
	s_add_i32 s8, s8, 1
	s_cmp_lt_i32 s8, 0
	s_cbranch_scc1 .LBB0_837
	s_cmp_le_i32 s58, s83
	s_cbranch_scc1 .LBB0_837
	v_add_u32_e32 v0, s58, v196
	v_subrev_u32_e32 v167, 31, v0
	v_subrev_u32_e32 v166, 63, v0
	v_cmp_le_i32_e32 vcc, v167, v200
	s_nop 1
	v_cndmask_b32_e32 v66, v190, v66, vcc
	v_cmp_lt_i32_e32 vcc, v166, v200
	s_nop 1
	v_cndmask_b32_e32 v83, v190, v83, vcc
	v_cmp_le_i32_e32 vcc, v166, v200
	v_subrev_u32_e32 v166, 30, v0
	s_nop 0
	v_cndmask_b32_e32 v82, v190, v82, vcc
	v_cmp_le_i32_e32 vcc, v166, v200
	v_subrev_u32_e32 v166, 61, v0
	s_nop 0
	v_cndmask_b32_e32 v67, v190, v67, vcc
	v_cmp_le_i32_e32 vcc, v166, v200
	v_subrev_u32_e32 v166, 29, v0
	s_nop 0
	v_cndmask_b32_e32 v84, v190, v84, vcc
	v_cmp_le_i32_e32 vcc, v166, v200
	v_subrev_u32_e32 v166, 60, v0
	s_nop 0
	v_cndmask_b32_e32 v68, v190, v68, vcc
	v_cmp_le_i32_e32 vcc, v166, v200
	v_subrev_u32_e32 v166, 28, v0
	s_nop 0
	v_cndmask_b32_e32 v85, v190, v85, vcc
	v_cmp_le_i32_e32 vcc, v166, v200
	v_subrev_u32_e32 v166, 55, v0
	s_nop 0
	v_cndmask_b32_e32 v69, v190, v69, vcc
	v_cmp_le_i32_e32 vcc, v166, v200
	v_subrev_u32_e32 v166, 23, v0
	s_nop 0
	v_cndmask_b32_e32 v86, v190, v86, vcc
	v_cmp_le_i32_e32 vcc, v166, v200
	v_subrev_u32_e32 v166, 54, v0
	s_nop 0
	v_cndmask_b32_e32 v70, v190, v70, vcc
	v_cmp_le_i32_e32 vcc, v166, v200
	v_subrev_u32_e32 v166, 22, v0
	s_nop 0
	v_cndmask_b32_e32 v87, v190, v87, vcc
	v_cmp_le_i32_e32 vcc, v166, v200
	v_subrev_u32_e32 v166, 53, v0
	s_nop 0
	v_cndmask_b32_e32 v71, v190, v71, vcc
	v_cmp_le_i32_e32 vcc, v166, v200
	v_subrev_u32_e32 v166, 21, v0
	s_nop 0
	v_cndmask_b32_e32 v88, v190, v88, vcc
	v_cmp_le_i32_e32 vcc, v166, v200
	v_subrev_u32_e32 v166, 52, v0
	s_nop 0
	v_cndmask_b32_e32 v72, v190, v72, vcc
	v_cmp_le_i32_e32 vcc, v166, v200
	v_subrev_u32_e32 v166, 20, v0
	s_nop 0
	v_cndmask_b32_e32 v89, v190, v89, vcc
	v_cmp_le_i32_e32 vcc, v166, v200
	v_subrev_u32_e32 v166, 47, v0
	s_nop 0
	v_cndmask_b32_e32 v73, v190, v73, vcc
	v_cmp_le_i32_e32 vcc, v166, v200
	v_add_u32_e32 v166, -15, v0
	s_nop 0
	v_cndmask_b32_e32 v90, v190, v90, vcc
	v_cmp_le_i32_e32 vcc, v166, v200
	v_subrev_u32_e32 v166, 46, v0
	s_nop 0
	v_cndmask_b32_e32 v74, v190, v74, vcc
	v_cmp_le_i32_e32 vcc, v166, v200
	v_add_u32_e32 v166, -14, v0
	s_nop 0
	v_cndmask_b32_e32 v91, v190, v91, vcc
	v_cmp_le_i32_e32 vcc, v166, v200
	v_subrev_u32_e32 v166, 45, v0
	s_nop 0
	v_cndmask_b32_e32 v75, v190, v75, vcc
	v_cmp_le_i32_e32 vcc, v166, v200
	v_add_u32_e32 v166, -13, v0
	s_nop 0
	v_cndmask_b32_e32 v92, v190, v92, vcc
	v_cmp_le_i32_e32 vcc, v166, v200
	v_subrev_u32_e32 v166, 44, v0
	s_nop 0
	v_cndmask_b32_e32 v76, v190, v76, vcc
	v_cmp_le_i32_e32 vcc, v166, v200
	v_add_u32_e32 v166, -12, v0
	s_nop 0
	v_cndmask_b32_e32 v93, v190, v93, vcc
	v_cmp_le_i32_e32 vcc, v166, v200
	v_subrev_u32_e32 v166, 39, v0
	s_nop 0
	v_cndmask_b32_e32 v77, v190, v77, vcc
	v_cmp_le_i32_e32 vcc, v166, v200
	v_add_u32_e32 v166, -7, v0
	s_nop 0
	v_cndmask_b32_e32 v94, v190, v94, vcc
	v_cmp_le_i32_e32 vcc, v166, v200
	v_subrev_u32_e32 v166, 38, v0
	s_nop 0
	v_cndmask_b32_e32 v78, v190, v78, vcc
	v_cmp_le_i32_e32 vcc, v166, v200
	v_add_u32_e32 v166, -6, v0
	s_nop 0
	v_cndmask_b32_e32 v95, v190, v95, vcc
	v_cmp_le_i32_e32 vcc, v166, v200
	v_subrev_u32_e32 v166, 37, v0
	s_nop 0
	v_cndmask_b32_e32 v79, v190, v79, vcc
	v_cmp_le_i32_e32 vcc, v166, v200
	v_add_u32_e32 v166, -5, v0
	s_nop 0
	v_cndmask_b32_e32 v96, v190, v96, vcc
	v_cmp_le_i32_e32 vcc, v166, v200
	v_subrev_u32_e32 v166, 36, v0
	v_add_u32_e32 v0, -4, v0
	v_cndmask_b32_e32 v80, v190, v80, vcc
	v_cmp_le_i32_e32 vcc, v166, v200
	s_nop 1
	v_cndmask_b32_e32 v97, v190, v97, vcc
	v_cmp_le_i32_e32 vcc, v0, v200
	s_nop 1
	v_cndmask_b32_e32 v81, v190, v81, vcc
.LBB0_837:
	v_max_f32_e32 v0, v83, v83
	v_max_f32_e32 v166, v82, v82
	v_max_f32_e32 v0, v166, v0
	v_max3_f32 v0, v0, v84, v85
	v_max3_f32 v0, v0, v86, v87
	v_max3_f32 v0, v0, v88, v89
	v_max3_f32 v0, v0, v90, v91
	v_max3_f32 v0, v0, v92, v93
	v_max3_f32 v0, v0, v94, v95
	v_max3_f32 v0, v0, v96, v97
	v_max3_f32 v0, v0, v66, v67
	v_max3_f32 v0, v0, v68, v69
	v_max3_f32 v0, v0, v70, v71
	v_max3_f32 v0, v0, v72, v73
	v_max3_f32 v0, v0, v74, v75
	v_max3_f32 v0, v0, v76, v77
	v_max3_f32 v0, v0, v78, v79
	v_max3_f32 v0, v0, v80, v81
	v_mov_b32_e32 v166, v0
	s_nop 1
	v_permlane32_swap_b32_e32 v0, v166
	v_max_f32_e32 v166, v166, v166
	v_max_f32_e32 v0, v0, v0
	v_max_f32_e32 v0, v0, v166
	v_max_f32_e32 v166, v203, v203
	v_max_f32_e32 v166, v166, v0
	v_sub_f32_e32 v167, v0, v203
	v_sub_f32_e32 v0, v203, v166
	v_exp_f32_e32 v0, v0
	v_cmp_ge_f32_e32 vcc, s77, v167
	s_cmp_eq_u64 vcc, exec
	s_cselect_b64 s[8:9], -1, 0
	v_cndmask_b32_e64 v206, v0, 1.0, s[8:9]
	v_cmp_gt_f32_e32 vcc, 1.0, v206
	s_cbranch_vccz .LBB0_841
	v_pk_mul_f32 v[30:31], v[30:31], v[206:207] op_sel_hi:[1,0]
	v_pk_mul_f32 v[26:27], v[26:27], v[206:207] op_sel_hi:[1,0]
	v_pk_mul_f32 v[22:23], v[22:23], v[206:207] op_sel_hi:[1,0]
	v_pk_mul_f32 v[32:33], v[32:33], v[206:207] op_sel_hi:[1,0]
	v_pk_mul_f32 v[28:29], v[28:29], v[206:207] op_sel_hi:[1,0]
	v_pk_mul_f32 v[24:25], v[24:25], v[206:207] op_sel_hi:[1,0]
	v_pk_mul_f32 v[20:21], v[20:21], v[206:207] op_sel_hi:[1,0]
	v_pk_mul_f32 v[18:19], v[18:19], v[206:207] op_sel_hi:[1,0]
	v_pk_mul_f32 v[46:47], v[46:47], v[206:207] op_sel_hi:[1,0]
	v_pk_mul_f32 v[42:43], v[42:43], v[206:207] op_sel_hi:[1,0]
	v_pk_mul_f32 v[38:39], v[38:39], v[206:207] op_sel_hi:[1,0]
	v_pk_mul_f32 v[48:49], v[48:49], v[206:207] op_sel_hi:[1,0]
	v_pk_mul_f32 v[44:45], v[44:45], v[206:207] op_sel_hi:[1,0]
	v_pk_mul_f32 v[40:41], v[40:41], v[206:207] op_sel_hi:[1,0]
	v_pk_mul_f32 v[36:37], v[36:37], v[206:207] op_sel_hi:[1,0]
	v_pk_mul_f32 v[34:35], v[34:35], v[206:207] op_sel_hi:[1,0]
	v_pk_mul_f32 v[62:63], v[62:63], v[206:207] op_sel_hi:[1,0]
	v_pk_mul_f32 v[58:59], v[58:59], v[206:207] op_sel_hi:[1,0]
	v_pk_mul_f32 v[54:55], v[54:55], v[206:207] op_sel_hi:[1,0]
	v_pk_mul_f32 v[64:65], v[64:65], v[206:207] op_sel_hi:[1,0]
	v_pk_mul_f32 v[60:61], v[60:61], v[206:207] op_sel_hi:[1,0]
	v_pk_mul_f32 v[56:57], v[56:57], v[206:207] op_sel_hi:[1,0]
	v_pk_mul_f32 v[52:53], v[52:53], v[206:207] op_sel_hi:[1,0]
	v_pk_mul_f32 v[50:51], v[50:51], v[206:207] op_sel_hi:[1,0]
	v_pk_mul_f32 v[14:15], v[14:15], v[206:207] op_sel_hi:[1,0]
	v_pk_mul_f32 v[10:11], v[10:11], v[206:207] op_sel_hi:[1,0]
	v_pk_mul_f32 v[6:7], v[6:7], v[206:207] op_sel_hi:[1,0]
	v_pk_mul_f32 v[16:17], v[16:17], v[206:207] op_sel_hi:[1,0]
	v_pk_mul_f32 v[12:13], v[12:13], v[206:207] op_sel_hi:[1,0]
	v_pk_mul_f32 v[8:9], v[8:9], v[206:207] op_sel_hi:[1,0]
	v_pk_mul_f32 v[4:5], v[4:5], v[206:207] op_sel_hi:[1,0]
	v_pk_mul_f32 v[2:3], v[2:3], v[206:207] op_sel_hi:[1,0]

; #define ATT_SBAR() __builtin_amdgcn_sched_barrier(0)
; #define PV_RD(D0, X) do { X[0] = PV_TRB(v_rd_off(D0, 0, 0)); X[1] = PV_TRB(v_rd_off(D0, 0, 1)); X[2] = PV_TRB(v_rd_off(D0, 1, 0)); X[3] = PV_TRB(v_rd_off(D0, 1, 1)); \
;                           X[4] = PV_TRB(v_rd_off(D0, 2, 0)); X[5] = PV_TRB(v_rd_off(D0, 2, 1)); X[6] = PV_TRB(v_rd_off(D0, 3, 0)); X[7] = PV_TRB(v_rd_off(D0, 3, 1)); } while (0)
; __device__ __forceinline__ void pv_d0(f32x16* o, int vb, bf16x8 pa0, bf16x8 pa1, bf16x8 pa2, bf16x8 pa3) {
;     ...
;     s16x4 F[8], G[8];
;     PV_RD(0, F); ATT_SBAR();
;     PV_RD(1, G); ATT_SBAR(); PV_MM(0, F); ATT_SBAR();
;     PV_RD(2, F); ATT_SBAR(); PV_MM(1, G); ATT_SBAR();
;     PV_RD(3, G); ATT_SBAR(); PV_MM(2, F); ATT_SBAR();
;     PV_MM(3, G);
;     ...
; }
.LBB0_849:
	ds_read_b64_tr_b16 v[66:67], v197 offset:16384
	ds_read_b64_tr_b16 v[68:69], v197 offset:18432
	ds_read_b64_tr_b16 v[70:71], v197 offset:20480
	ds_read_b64_tr_b16 v[72:73], v197 offset:22528
	ds_read_b64_tr_b16 v[74:75], v197 offset:24576
	ds_read_b64_tr_b16 v[76:77], v197 offset:26624
	ds_read_b64_tr_b16 v[78:79], v197 offset:28672
	ds_read_b64_tr_b16 v[80:81], v197 offset:30720
	ds_read_b64_tr_b16 v[82:83], v197 offset:16896
	ds_read_b64_tr_b16 v[84:85], v197 offset:18944
	ds_read_b64_tr_b16 v[86:87], v197 offset:20992
	ds_read_b64_tr_b16 v[88:89], v197 offset:23040
	ds_read_b64_tr_b16 v[90:91], v197 offset:25088
	ds_read_b64_tr_b16 v[92:93], v197 offset:27136
	ds_read_b64_tr_b16 v[94:95], v197 offset:29184
	ds_read_b64_tr_b16 v[96:97], v197 offset:31232
	s_waitcnt lgkmcnt(14)
	v_mfma_f32_32x32x16_bf16 v[18:33], v[66:69], v[166:169], v[18:33]
	s_waitcnt lgkmcnt(12)
	v_mfma_f32_32x32x16_bf16 v[18:33], v[70:73], v[170:173], v[18:33]
	s_waitcnt lgkmcnt(10)
	v_mfma_f32_32x32x16_bf16 v[18:33], v[74:77], v[174:177], v[18:33]
	s_waitcnt lgkmcnt(8)
	v_mfma_f32_32x32x16_bf16 v[18:33], v[78:81], v[178:181], v[18:33]
	ds_read_b64_tr_b16 v[66:67], v197 offset:17408
	ds_read_b64_tr_b16 v[68:69], v197 offset:19456
	ds_read_b64_tr_b16 v[70:71], v197 offset:21504
	ds_read_b64_tr_b16 v[72:73], v197 offset:23552
	ds_read_b64_tr_b16 v[74:75], v197 offset:25600
	ds_read_b64_tr_b16 v[76:77], v197 offset:27648
	ds_read_b64_tr_b16 v[78:79], v197 offset:29696
	ds_read_b64_tr_b16 v[80:81], v197 offset:31744
	s_waitcnt lgkmcnt(14)
	v_mfma_f32_32x32x16_bf16 v[34:49], v[82:85], v[166:169], v[34:49]
	s_waitcnt lgkmcnt(12)
	v_mfma_f32_32x32x16_bf16 v[34:49], v[86:89], v[170:173], v[34:49]
	s_waitcnt lgkmcnt(10)
	v_mfma_f32_32x32x16_bf16 v[34:49], v[90:93], v[174:177], v[34:49]
	s_waitcnt lgkmcnt(8)
	v_mfma_f32_32x32x16_bf16 v[34:49], v[94:97], v[178:181], v[34:49]
	ds_read_b64_tr_b16 v[82:83], v197 offset:17920
	ds_read_b64_tr_b16 v[84:85], v197 offset:19968
	ds_read_b64_tr_b16 v[86:87], v197 offset:22016
	ds_read_b64_tr_b16 v[88:89], v197 offset:24064
	ds_read_b64_tr_b16 v[90:91], v197 offset:26112
	ds_read_b64_tr_b16 v[92:93], v197 offset:28160
	ds_read_b64_tr_b16 v[94:95], v197 offset:30208
	ds_read_b64_tr_b16 v[96:97], v197 offset:32256
	s_waitcnt lgkmcnt(14)
	v_mfma_f32_32x32x16_bf16 v[50:65], v[66:69], v[166:169], v[50:65]
	s_waitcnt lgkmcnt(12)
	v_mfma_f32_32x32x16_bf16 v[50:65], v[70:73], v[170:173], v[50:65]
	s_waitcnt lgkmcnt(10)
	v_mfma_f32_32x32x16_bf16 v[50:65], v[74:77], v[174:177], v[50:65]
	s_waitcnt lgkmcnt(8)
	v_mfma_f32_32x32x16_bf16 v[50:65], v[78:81], v[178:181], v[50:65]
	s_waitcnt lgkmcnt(6)
	v_mfma_f32_32x32x16_bf16 v[2:17], v[82:85], v[166:169], v[2:17]
	s_waitcnt lgkmcnt(4)
	v_mfma_f32_32x32x16_bf16 v[2:17], v[86:89], v[170:173], v[2:17]
	s_waitcnt lgkmcnt(2)
	v_mfma_f32_32x32x16_bf16 v[2:17], v[90:93], v[174:177], v[2:17]
	s_waitcnt lgkmcnt(0)
	v_mfma_f32_32x32x16_bf16 v[2:17], v[94:97], v[178:181], v[2:17]
	s_waitcnt lgkmcnt(0)
	s_barrier
	s_waitcnt vmcnt(0)
	s_cmp_lt_i32 s11, -1
	s_cbranch_scc0 .LBB0_851
	v_add_u32_e32 v0, s82, v188
	s_waitcnt vmcnt(2)
	ds_write_b128 v0, v[146:149] offset:32768
	s_waitcnt vmcnt(1)
	ds_write_b128 v0, v[150:153] offset:45568
	v_add_u32_e32 v0, s82, v186
	s_waitcnt vmcnt(0)
	ds_write_b128 v0, v[154:157] offset:33024

; __device__ __forceinline__ unsigned cvt_pk_bf16(float lo, float hi) { unsigned r; asm volatile("v_cvt_pk_bf16_f32 %0, %1, %2" : "=v"(r) : "v"(lo), "v"(hi)); return r; }
; __device__ __forceinline__ int crow(int r, int hi) { return (r & 3) + 8 * (r >> 2) + 4 * hi; }
; template <int DK, bool CAUSAL> ...
;     ...
;     {
;         int t2 = threadIdx.x; asm volatile("" : "+v"(t2));
;         const int wid2 = t2 >> 6, r2 = t2 & 31, hi2 = (t2 >> 5) & 1;
;         float* li2 = (float*)(lds + 2 * SHM_V + 2 * SHM_K) + wid2 * 64;
;         if (hi2 == 0) li2[r2] = l_reg; asm volatile("s_waitcnt lgkmcnt(0)" ::: "memory");
;         bf16_t* Ow = O + (size_t)(wid2 * QBLK) * ldo + r2;
; #pragma unroll
;         for (int r = 0; r < 16; ++r) { const int orow = crow(r, hi2); const float rl = __builtin_amdgcn_rcpf(li2[orow]);
; #pragma unroll
;             for (int d0 = 0; d0 < 4; ++d0) { const unsigned w = cvt_pk_bf16(o[d0][r] * rl, 0.f); Ow[(size_t)orow * ldo + d0 * 32] = (bf16_t)(w & 0xffffu); } }
;     }
.LBB0_855:
	v_rcp_f32_e32 v78, v199
	v_and_b32_e32 v66, 31, v254
	v_lshrrev_b32_e32 v67, 6, v254
	v_bfe_u32 v68, v254, 5, 1
	v_mul_u32_u24_e32 v69, 0x2200, v67
	v_mov_b32_e32 v79, 0x110
	v_mad_u32_u24 v70, v66, v79, v69
	v_lshl_add_u32 v70, v68, 4, v70
	v_lshrrev_b32_e32 v71, 4, v254
	v_and_b32_e32 v71, 3, v71
	v_and_b32_e32 v73, 15, v254
	v_mad_u32_u24 v74, v71, v79, v69
	v_lshl_add_u32 v74, v73, 4, v74
	v_lshl_add_u32 v75, v67, 5, v71
	v_lshlrev_b32_e32 v76, 12, v75
	v_lshl_or_b32 v76, v73, 4, v76
	v_mov_b32_e32 v77, 0
	s_lshl_b64 s[0:1], s[62:63], 12
	s_add_u32 s0, s80, s0
	s_addc_u32 s1, s81, s1
	v_lshl_add_u64 v[76:77], s[0:1], 0, v[76:77]
	s_mov_b64 s[98:99], 0x4000
	v_pk_mul_f32 v[2:3], v[2:3], v[78:79] op_sel_hi:[1,0]
	v_pk_mul_f32 v[4:5], v[4:5], v[78:79] op_sel_hi:[1,0]
	v_pk_mul_f32 v[6:7], v[6:7], v[78:79] op_sel_hi:[1,0]
	v_pk_mul_f32 v[8:9], v[8:9], v[78:79] op_sel_hi:[1,0]
	v_pk_mul_f32 v[10:11], v[10:11], v[78:79] op_sel_hi:[1,0]
	v_pk_mul_f32 v[12:13], v[12:13], v[78:79] op_sel_hi:[1,0]
	v_pk_mul_f32 v[14:15], v[14:15], v[78:79] op_sel_hi:[1,0]
	v_pk_mul_f32 v[16:17], v[16:17], v[78:79] op_sel_hi:[1,0]
	v_pk_mul_f32 v[18:19], v[18:19], v[78:79] op_sel_hi:[1,0]
	v_pk_mul_f32 v[20:21], v[20:21], v[78:79] op_sel_hi:[1,0]
	v_pk_mul_f32 v[22:23], v[22:23], v[78:79] op_sel_hi:[1,0]
	v_pk_mul_f32 v[24:25], v[24:25], v[78:79] op_sel_hi:[1,0]
	v_pk_mul_f32 v[26:27], v[26:27], v[78:79] op_sel_hi:[1,0]
	v_pk_mul_f32 v[28:29], v[28:29], v[78:79] op_sel_hi:[1,0]
	v_pk_mul_f32 v[30:31], v[30:31], v[78:79] op_sel_hi:[1,0]
	v_pk_mul_f32 v[32:33], v[32:33], v[78:79] op_sel_hi:[1,0]
	v_pk_mul_f32 v[34:35], v[34:35], v[78:79] op_sel_hi:[1,0]
	v_pk_mul_f32 v[36:37], v[36:37], v[78:79] op_sel_hi:[1,0]
	v_pk_mul_f32 v[38:39], v[38:39], v[78:79] op_sel_hi:[1,0]
	v_pk_mul_f32 v[40:41], v[40:41], v[78:79] op_sel_hi:[1,0]
	v_pk_mul_f32 v[42:43], v[42:43], v[78:79] op_sel_hi:[1,0]
	v_pk_mul_f32 v[44:45], v[44:45], v[78:79] op_sel_hi:[1,0]
	v_pk_mul_f32 v[46:47], v[46:47], v[78:79] op_sel_hi:[1,0]
	v_pk_mul_f32 v[48:49], v[48:49], v[78:79] op_sel_hi:[1,0]
	v_pk_mul_f32 v[50:51], v[50:51], v[78:79] op_sel_hi:[1,0]
	v_pk_mul_f32 v[52:53], v[52:53], v[78:79] op_sel_hi:[1,0]
	v_pk_mul_f32 v[54:55], v[54:55], v[78:79] op_sel_hi:[1,0]
	v_pk_mul_f32 v[56:57], v[56:57], v[78:79] op_sel_hi:[1,0]
	v_pk_mul_f32 v[58:59], v[58:59], v[78:79] op_sel_hi:[1,0]
	v_pk_mul_f32 v[60:61], v[60:61], v[78:79] op_sel_hi:[1,0]
	v_pk_mul_f32 v[62:63], v[62:63], v[78:79] op_sel_hi:[1,0]
	v_pk_mul_f32 v[64:65], v[64:65], v[78:79] op_sel_hi:[1,0]
	v_cvt_pk_bf16_f32 v204, v18, v19
	v_cvt_pk_bf16_f32 v205, v20, v21
	v_cvt_pk_bf16_f32 v206, v22, v23
	v_cvt_pk_bf16_f32 v207, v24, v25
	s_nop 1
	v_permlane32_swap_b32_e32 v204, v206
	v_permlane32_swap_b32_e32 v205, v207
	ds_write_b128 v70, v[204:207]
	v_cvt_pk_bf16_f32 v208, v26, v27
	v_cvt_pk_bf16_f32 v209, v28, v29
	v_cvt_pk_bf16_f32 v210, v30, v31
	v_cvt_pk_bf16_f32 v211, v32, v33
	s_nop 1
	v_permlane32_swap_b32_e32 v208, v210
	v_permlane32_swap_b32_e32 v209, v211
	ds_write_b128 v70, v[208:211] offset:32
	v_cvt_pk_bf16_f32 v204, v34, v35
	v_cvt_pk_bf16_f32 v205, v36, v37
	v_cvt_pk_bf16_f32 v206, v38, v39
	v_cvt_pk_bf16_f32 v207, v40, v41
	s_nop 1
	v_permlane32_swap_b32_e32 v204, v206
	v_permlane32_swap_b32_e32 v205, v207
	ds_write_b128 v70, v[204:207] offset:64
	v_cvt_pk_bf16_f32 v208, v42, v43
	v_cvt_pk_bf16_f32 v209, v44, v45
	v_cvt_pk_bf16_f32 v210, v46, v47
	v_cvt_pk_bf16_f32 v211, v48, v49
	s_nop 1
	v_permlane32_swap_b32_e32 v208, v210
	v_permlane32_swap_b32_e32 v209, v211
	ds_write_b128 v70, v[208:211] offset:96
	v_cvt_pk_bf16_f32 v204, v50, v51
	v_cvt_pk_bf16_f32 v205, v52, v53
	v_cvt_pk_bf16_f32 v206, v54, v55
	v_cvt_pk_bf16_f32 v207, v56, v57
	s_nop 1
	v_permlane32_swap_b32_e32 v204, v206
	v_permlane32_swap_b32_e32 v205, v207
	ds_write_b128 v70, v[204:207] offset:128
	v_cvt_pk_bf16_f32 v208, v58, v59
	v_cvt_pk_bf16_f32 v209, v60, v61
	v_cvt_pk_bf16_f32 v210, v62, v63
	v_cvt_pk_bf16_f32 v211, v64, v65
	s_nop 1
	v_permlane32_swap_b32_e32 v208, v210
	v_permlane32_swap_b32_e32 v209, v211
	ds_write_b128 v70, v[208:211] offset:160
	v_cvt_pk_bf16_f32 v204, v2, v3
	v_cvt_pk_bf16_f32 v205, v4, v5
	v_cvt_pk_bf16_f32 v206, v6, v7
	v_cvt_pk_bf16_f32 v207, v8, v9
	s_nop 1
	v_permlane32_swap_b32_e32 v204, v206
	v_permlane32_swap_b32_e32 v205, v207
	ds_write_b128 v70, v[204:207] offset:192
	v_cvt_pk_bf16_f32 v208, v10, v11
	v_cvt_pk_bf16_f32 v209, v12, v13
	v_cvt_pk_bf16_f32 v210, v14, v15
	v_cvt_pk_bf16_f32 v211, v16, v17
	s_nop 1
	v_permlane32_swap_b32_e32 v208, v210
	v_permlane32_swap_b32_e32 v209, v211
	ds_write_b128 v70, v[208:211] offset:224
	s_waitcnt lgkmcnt(0)
	ds_read_b128 v[100:103], v74
	ds_read_b128 v[104:107], v74 offset:1088
	ds_read_b128 v[108:111], v74 offset:2176
	ds_read_b128 v[112:115], v74 offset:3264
	ds_read_b128 v[116:119], v74 offset:4352
	ds_read_b128 v[120:123], v74 offset:5440
	ds_read_b128 v[124:127], v74 offset:6528
	ds_read_b128 v[128:131], v74 offset:7616
	s_waitcnt lgkmcnt(7)
	global_store_dwordx4 v[76:77], v[100:103], off
	v_lshl_add_u64 v[76:77], v[76:77], 0, s[98:99]
	s_waitcnt lgkmcnt(6)
	global_store_dwordx4 v[76:77], v[104:107], off
	v_lshl_add_u64 v[76:77], v[76:77], 0, s[98:99]
	s_waitcnt lgkmcnt(5)
	global_store_dwordx4 v[76:77], v[108:111], off
	v_lshl_add_u64 v[76:77], v[76:77], 0, s[98:99]
	s_waitcnt lgkmcnt(4)
	global_store_dwordx4 v[76:77], v[112:115], off
	v_lshl_add_u64 v[76:77], v[76:77], 0, s[98:99]
	s_waitcnt lgkmcnt(3)
	global_store_dwordx4 v[76:77], v[116:119], off
	v_lshl_add_u64 v[76:77], v[76:77], 0, s[98:99]
	s_waitcnt lgkmcnt(2)
	global_store_dwordx4 v[76:77], v[120:123], off
	v_lshl_add_u64 v[76:77], v[76:77], 0, s[98:99]
	s_waitcnt lgkmcnt(1)
	global_store_dwordx4 v[76:77], v[124:127], off
	v_lshl_add_u64 v[76:77], v[76:77], 0, s[98:99]
	s_waitcnt lgkmcnt(0)
	global_store_dwordx4 v[76:77], v[128:131], off
	s_branch .LBB0_781

; __global__ void __launch_bounds__(NWAVES * 64, 2) mk_fwd(Params P) {
	.amdhsa_kernel _Z6mk_fwd6Params
		.amdhsa_group_segment_fixed_size 0
		.amdhsa_private_segment_fixed_size 0
		.amdhsa_kernarg_size 528
		.amdhsa_user_sgpr_count 2
		.amdhsa_user_sgpr_dispatch_ptr 0
		.amdhsa_user_sgpr_queue_ptr 0
		.amdhsa_user_sgpr_kernarg_segment_ptr 1
		.amdhsa_user_sgpr_dispatch_id 0
		.amdhsa_user_sgpr_kernarg_preload_length 0
		.amdhsa_user_sgpr_kernarg_preload_offset 0
		.amdhsa_user_sgpr_private_segment_size 0
		.amdhsa_uses_dynamic_stack 0
		.amdhsa_enable_private_segment 0
		.amdhsa_system_sgpr_workgroup_id_x 1
		.amdhsa_system_sgpr_workgroup_id_y 0
		.amdhsa_system_sgpr_workgroup_id_z 0
		.amdhsa_system_sgpr_workgroup_info 0
		.amdhsa_system_vgpr_workitem_id 0
		.amdhsa_next_free_vgpr 256
		.amdhsa_next_free_sgpr 102
		.amdhsa_accum_offset 256
		.amdhsa_reserve_vcc 1
		.amdhsa_float_round_mode_32 0
		.amdhsa_float_round_mode_16_64 0
		.amdhsa_float_denorm_mode_32 3
		.amdhsa_float_denorm_mode_16_64 3
		.amdhsa_dx10_clamp 1
		.amdhsa_ieee_mode 1
		.amdhsa_fp16_overflow 0
		.amdhsa_tg_split 0
		.amdhsa_exception_fp_ieee_invalid_op 0
		.amdhsa_exception_fp_denorm_src 0
		.amdhsa_exception_fp_ieee_div_zero 0
		.amdhsa_exception_fp_ieee_overflow 0
		.amdhsa_exception_fp_ieee_underflow 0
		.amdhsa_exception_fp_ieee_inexact 0
		.amdhsa_exception_int_div_zero 0
	.end_amdhsa_kernel

; __global__ void __launch_bounds__(NWAVES * 64, 2) mk_fwd(Params P) {
amdhsa.kernels:
  - .agpr_count:     0
    .args:
      - .offset:         0
        .size:           272
        .value_kind:     by_value
      - .offset:         272
        .size:           4
        .value_kind:     hidden_block_count_x
      - .offset:         276
        .size:           4
        .value_kind:     hidden_block_count_y
      - .offset:         280
        .size:           4
        .value_kind:     hidden_block_count_z
      - .offset:         284
        .size:           2
        .value_kind:     hidden_group_size_x
      - .offset:         286
        .size:           2
        .value_kind:     hidden_group_size_y
      - .offset:         288
        .size:           2
        .value_kind:     hidden_group_size_z
      - .offset:         290
        .size:           2
        .value_kind:     hidden_remainder_x
      - .offset:         292
        .size:           2
        .value_kind:     hidden_remainder_y
      - .offset:         294
        .size:           2
        .value_kind:     hidden_remainder_z
      - .offset:         312
        .size:           8
        .value_kind:     hidden_global_offset_x
      - .offset:         320
        .size:           8
        .value_kind:     hidden_global_offset_y
      - .offset:         328
        .size:           8
        .value_kind:     hidden_global_offset_z
      - .offset:         336
        .size:           2
        .value_kind:     hidden_grid_dims
      - .offset:         392
        .size:           4
        .value_kind:     hidden_dynamic_lds_size
    .group_segment_fixed_size: 0
    .kernarg_segment_align: 8
    .kernarg_segment_size: 528
    .language:       OpenCL C
    .language_version:
      - 2
      - 0
    .max_flat_workgroup_size: 512
    .name:           _Z6mk_fwd6Params
    .private_segment_fixed_size: 0
    .sgpr_count:     108
    .sgpr_spill_count: 30
    .symbol:         _Z6mk_fwd6Params.kd
    .uniform_work_group_size: 1
    .uses_dynamic_stack: false
    .vgpr_count:     256
    .vgpr_spill_count: 0
    .wavefront_size: 64
